# W_o and down GEMM phases: third 16-tile round replaced by a 64x64-per-workgroup K-sliced tail (LDS reduction); LN loops prefetched
# speedup vs baseline: 1.0456x; 1.0393x over previous
.LBB0_566:
	s_or_b64 exec, exec, s[0:1]
	s_mov_b64 s[0:1], s[94:95]
	s_mov_b64 s[4:5], s[36:37]
	s_waitcnt lgkmcnt(0)
	s_barrier
	v_readlane_b32 s2, v255, 36
	v_readlane_b32 s0, v255, 0
	s_add_i32 s0, s0, s84
	s_ashr_i32 s1, s0, 31
	s_abs_i32 s0, s0
	s_mul_hi_u32 s2, s0, s2
	s_mul_i32 s2, s2, s60
	s_sub_i32 s0, s0, s2
	s_sub_i32 s2, s0, s60
	s_cmp_ge_u32 s0, s60
	s_cselect_b32 s0, s2, s0
	s_sub_i32 s2, s0, s60
	s_cmp_ge_u32 s0, s60
	s_cselect_b32 s0, s2, s0
	s_xor_b32 s0, s0, s1
	s_sub_i32 s2, s0, s1
	s_cmpk_gt_i32 s2, 0x20f
	s_cbranch_scc1 .LBB0_577
	s_add_u32 s6, s4, 0x44c4000
	s_addc_u32 s7, s5, 0
	s_add_u32 s39, s4, 0x86c4000
	s_addc_u32 s50, s5, 0
	s_add_u32 s8, s4, 0xc8c4000
	s_addc_u32 s9, s5, 0
	s_add_u32 s51, s4, 0xfc4000
	s_addc_u32 s52, s5, 0
	s_ashr_i32 s53, s2, 31
	s_lshr_b32 s0, s53, 29
	s_add_i32 s0, s2, s0
	s_ashr_i32 s1, s0, 3
	s_and_b32 s0, s0, -8
	s_sub_i32 s0, s2, s0
	s_cmp_lt_i32 s0, 0
	s_movk_i32 s54, 0x43
	s_cselect_b32 s10, s54, 0x42
	s_mul_i32 s0, s10, s0
	s_add_i32 s0, s0, s1
	s_ashr_i32 s1, s0, 31
	s_lshr_b32 s1, s1, 27
	s_add_i32 s1, s0, s1
	s_ashr_i32 s10, s1, 5
	s_andn2_b32 s1, s1, 31
	s_lshl_b32 s10, s10, 3
	s_sub_i32 s11, s0, s1
	s_sub_i32 s0, 0x84, s10
	s_min_u32 s12, s0, 8
	v_cvt_f32_ubyte0_e32 v1, s12
	v_cvt_f32_i32_e32 v0, s11
	v_rcp_iflag_f32_e32 v2, v1
	s_ashr_i32 s0, s11, 30
	s_or_b32 s13, s0, 1
	s_mov_b32 s55, 0
	v_mul_f32_e32 v2, v0, v2
	v_trunc_f32_e32 v2, v2
	v_fma_f32 v0, -v2, v1, v0
	v_cvt_i32_f32_e32 v2, v2
	v_cmp_ge_f32_e64 s[0:1], |v0|, v1
	s_and_b64 s[0:1], s[0:1], exec
	s_cselect_b32 s0, s13, 0
	v_readfirstlane_b32 s1, v2
	s_add_i32 s0, s1, s0
	s_sext_i32_i8 s43, s0
	s_mul_i32 s0, s0, s12
	s_sub_i32 s0, s11, s0
	s_sext_i32_i8 s0, s0
	s_add_i32 s42, s10, s0
	v_mov_b64_e32 v[128:129], 0x1ff
	s_mov_b64 s[10:11], 0x80
	s_movk_i32 s56, 0x3c0
	s_mov_b64 s[12:13], 0x8704080
	s_mov_b64 s[14:15], 0xfc4100
	s_mov_b64 s[16:17], 0x86c4100
	s_mov_b64 s[18:19], 0x1004100
	s_mov_b64 s[20:21], 0x8704100
	s_mov_b64 s[22:23], 0xfc4180
	s_mov_b64 s[24:25], 0x86c4180
	s_mov_b64 s[26:27], 0x1004180
	s_mov_b64 s[28:29], 0x100
	s_mov_b64 s[30:31], 0x780
	s_movk_i32 s57, 0x100
	v_mov_b32_e32 v131, 0
	s_mov_b32 s38, 0x3fb504f3
	v_mov_b32_e32 v144, 1
	s_branch .LBB0_569

.LBB0_577:
	s_barrier
	v_readlane_b32 s16, v255, 0
	s_nop 3
	s_and_b32 s24, s16, 7
	s_lshr_b32 s17, s16, 3
	s_lshr_b32 s25, s17, 4
	s_and_b32 s17, s17, 15
	s_mul_i32 s24, s24, 0x42
	s_add_i32 s24, s24, s25
	s_add_i32 s24, s24, 64
	s_lshr_b32 s25, s24, 5
	s_lshl_b32 s25, s25, 3
	s_and_b32 s24, s24, 31
	s_cmp_eq_u32 s25, 0x80
	s_cbranch_scc1 .Ltail1_g4
	s_and_b32 s26, s24, 7
	s_lshr_b32 s27, s24, 3
	s_branch .Ltail1_gd
.Ltail1_g4:
	s_and_b32 s26, s24, 3
	s_lshr_b32 s27, s24, 2
.Ltail1_gd:
	s_add_i32 s26, s26, s25
	s_lshr_b32 s25, s17, 2
	s_and_b32 s24, s17, 3
	s_lshl_b32 s26, s26, 8
	s_lshl_b32 s25, s25, 6
	s_add_i32 s26, s26, s25
	s_lshl_b32 s27, s27, 8
	s_lshl_b32 s24, s24, 6
	s_add_i32 s27, s27, s24
	s_add_u32 s4, s36, 0x86c4000
	s_addc_u32 s5, s37, 0
	s_add_u32 s6, s36, 0xfc4000
	s_addc_u32 s7, s37, 0
	s_add_u32 s8, s36, 0x44c4000
	s_addc_u32 s9, s37, 0
	s_add_u32 s10, s36, 0xc8c4000
	s_addc_u32 s11, s37, 0
	s_mov_b32 s12, 0x3fb504f3
	s_mov_b32 s13, 0
	s_mov_b32 s17, 0x800
	v_and_b32_e32 v140, 63, v154
	v_lshrrev_b32_e32 v141, 6, v154
	v_and_b32_e32 v142, 15, v140
	v_lshrrev_b32_e32 v143, 4, v140
	v_mul_u32_u24_e32 v139, 0x100, v141
	v_lshl_add_u32 v139, v143, 4, v139
	v_add_u32_e32 v128, s26, v142
	v_mul_lo_u32 v128, v128, s17
	v_add_u32_e32 v128, v128, v139
	v_add_u32_e32 v129, 0x8000, v128
	v_add_u32_e32 v130, 0x10000, v128
	v_add_u32_e32 v131, 0x18000, v128
	v_add_u32_e32 v132, s27, v142
	v_mul_lo_u32 v132, v132, s17
	v_add_u32_e32 v132, v132, v139
	v_add_u32_e32 v133, 0x8000, v132
	v_add_u32_e32 v134, 0x10000, v132
	v_add_u32_e32 v135, 0x18000, v132
	v_lshrrev_b32_e32 v138, 1, v141
	v_lshl_add_u32 v138, v138, 4, v142
	v_add_u32_e32 v138, s26, v138
	v_lshlrev_b32_e32 v138, 11, v138
	v_and_b32_e32 v139, 1, v141
	v_lshlrev_b32_e32 v139, 6, v139
	v_lshl_add_u32 v139, v143, 3, v139
	s_lshl_b32 s16, s27, 1
	v_add3_u32 v139, v138, v139, s16
	global_load_dwordx2 v[208:209], v139, s[8:9]
	global_load_dwordx2 v[210:211], v139, s[8:9] offset:32
	v_lshlrev_b32_e32 v136, 4, v154
	v_add_u32_e32 v137, 0x10000, v136
	v_lshlrev_b32_e32 v138, 4, v140
	v_lshl_add_u32 v138, v141, 14, v138
	global_load_dwordx4 v[64:67], v128, s[4:5]
	global_load_dwordx4 v[68:71], v129, s[4:5]
	global_load_dwordx4 v[72:75], v130, s[4:5]
	global_load_dwordx4 v[76:79], v131, s[4:5]
	global_load_dwordx4 v[80:83], v132, s[6:7]
	global_load_dwordx4 v[84:87], v133, s[6:7]
	global_load_dwordx4 v[88:91], v134, s[6:7]
	global_load_dwordx4 v[92:95], v135, s[6:7]
	global_load_dwordx4 v[96:99], v128, s[4:5] offset:64
	global_load_dwordx4 v[100:103], v129, s[4:5] offset:64
	global_load_dwordx4 v[104:107], v130, s[4:5] offset:64
	global_load_dwordx4 v[108:111], v131, s[4:5] offset:64
	global_load_dwordx4 v[112:115], v132, s[6:7] offset:64
	global_load_dwordx4 v[116:119], v133, s[6:7] offset:64
	global_load_dwordx4 v[120:123], v134, s[6:7] offset:64
	global_load_dwordx4 v[124:127], v135, s[6:7] offset:64
	global_load_dwordx4 v[176:179], v128, s[4:5] offset:128
	global_load_dwordx4 v[180:183], v129, s[4:5] offset:128
	global_load_dwordx4 v[184:187], v130, s[4:5] offset:128
	global_load_dwordx4 v[188:191], v131, s[4:5] offset:128
	global_load_dwordx4 v[192:195], v132, s[6:7] offset:128
	global_load_dwordx4 v[196:199], v133, s[6:7] offset:128
	global_load_dwordx4 v[200:203], v134, s[6:7] offset:128
	global_load_dwordx4 v[204:207], v135, s[6:7] offset:128
	s_waitcnt vmcnt(16)
	v_mfma_f32_16x16x32_bf16 v[0:3], v[80:83], v[64:67], 0
	v_mfma_f32_16x16x32_bf16 v[4:7], v[84:87], v[64:67], 0
	v_mfma_f32_16x16x32_bf16 v[8:11], v[88:91], v[64:67], 0
	v_mfma_f32_16x16x32_bf16 v[12:15], v[92:95], v[64:67], 0
	v_mfma_f32_16x16x32_bf16 v[16:19], v[80:83], v[68:71], 0
	v_mfma_f32_16x16x32_bf16 v[20:23], v[84:87], v[68:71], 0
	v_mfma_f32_16x16x32_bf16 v[24:27], v[88:91], v[68:71], 0
	v_mfma_f32_16x16x32_bf16 v[28:31], v[92:95], v[68:71], 0
	v_mfma_f32_16x16x32_bf16 v[32:35], v[80:83], v[72:75], 0
	v_mfma_f32_16x16x32_bf16 v[36:39], v[84:87], v[72:75], 0
	v_mfma_f32_16x16x32_bf16 v[40:43], v[88:91], v[72:75], 0
	v_mfma_f32_16x16x32_bf16 v[44:47], v[92:95], v[72:75], 0
	v_mfma_f32_16x16x32_bf16 v[48:51], v[80:83], v[76:79], 0
	v_mfma_f32_16x16x32_bf16 v[52:55], v[84:87], v[76:79], 0
	v_mfma_f32_16x16x32_bf16 v[56:59], v[88:91], v[76:79], 0
	v_mfma_f32_16x16x32_bf16 v[60:63], v[92:95], v[76:79], 0
	global_load_dwordx4 v[64:67], v128, s[4:5] offset:192
	global_load_dwordx4 v[68:71], v129, s[4:5] offset:192
	global_load_dwordx4 v[72:75], v130, s[4:5] offset:192
	global_load_dwordx4 v[76:79], v131, s[4:5] offset:192
	global_load_dwordx4 v[80:83], v132, s[6:7] offset:192
	global_load_dwordx4 v[84:87], v133, s[6:7] offset:192
	global_load_dwordx4 v[88:91], v134, s[6:7] offset:192
	global_load_dwordx4 v[92:95], v135, s[6:7] offset:192
	s_waitcnt vmcnt(16)
	v_mfma_f32_16x16x32_bf16 v[0:3], v[112:115], v[96:99], v[0:3]
	v_mfma_f32_16x16x32_bf16 v[4:7], v[116:119], v[96:99], v[4:7]
	v_mfma_f32_16x16x32_bf16 v[8:11], v[120:123], v[96:99], v[8:11]
	v_mfma_f32_16x16x32_bf16 v[12:15], v[124:127], v[96:99], v[12:15]
	v_mfma_f32_16x16x32_bf16 v[16:19], v[112:115], v[100:103], v[16:19]
	v_mfma_f32_16x16x32_bf16 v[20:23], v[116:119], v[100:103], v[20:23]
	v_mfma_f32_16x16x32_bf16 v[24:27], v[120:123], v[100:103], v[24:27]
	v_mfma_f32_16x16x32_bf16 v[28:31], v[124:127], v[100:103], v[28:31]
	v_mfma_f32_16x16x32_bf16 v[32:35], v[112:115], v[104:107], v[32:35]
	v_mfma_f32_16x16x32_bf16 v[36:39], v[116:119], v[104:107], v[36:39]
	v_mfma_f32_16x16x32_bf16 v[40:43], v[120:123], v[104:107], v[40:43]
	v_mfma_f32_16x16x32_bf16 v[44:47], v[124:127], v[104:107], v[44:47]
	v_mfma_f32_16x16x32_bf16 v[48:51], v[112:115], v[108:111], v[48:51]
	v_mfma_f32_16x16x32_bf16 v[52:55], v[116:119], v[108:111], v[52:55]
	v_mfma_f32_16x16x32_bf16 v[56:59], v[120:123], v[108:111], v[56:59]
	v_mfma_f32_16x16x32_bf16 v[60:63], v[124:127], v[108:111], v[60:63]
	s_waitcnt vmcnt(8)
	v_mfma_f32_16x16x32_bf16 v[0:3], v[192:195], v[176:179], v[0:3]
	v_mfma_f32_16x16x32_bf16 v[4:7], v[196:199], v[176:179], v[4:7]
	v_mfma_f32_16x16x32_bf16 v[8:11], v[200:203], v[176:179], v[8:11]
	v_mfma_f32_16x16x32_bf16 v[12:15], v[204:207], v[176:179], v[12:15]
	v_mfma_f32_16x16x32_bf16 v[16:19], v[192:195], v[180:183], v[16:19]
	v_mfma_f32_16x16x32_bf16 v[20:23], v[196:199], v[180:183], v[20:23]
	v_mfma_f32_16x16x32_bf16 v[24:27], v[200:203], v[180:183], v[24:27]
	v_mfma_f32_16x16x32_bf16 v[28:31], v[204:207], v[180:183], v[28:31]
	v_mfma_f32_16x16x32_bf16 v[32:35], v[192:195], v[184:187], v[32:35]
	v_mfma_f32_16x16x32_bf16 v[36:39], v[196:199], v[184:187], v[36:39]
	v_mfma_f32_16x16x32_bf16 v[40:43], v[200:203], v[184:187], v[40:43]
	v_mfma_f32_16x16x32_bf16 v[44:47], v[204:207], v[184:187], v[44:47]
	v_mfma_f32_16x16x32_bf16 v[48:51], v[192:195], v[188:191], v[48:51]
	v_mfma_f32_16x16x32_bf16 v[52:55], v[196:199], v[188:191], v[52:55]
	v_mfma_f32_16x16x32_bf16 v[56:59], v[200:203], v[188:191], v[56:59]
	v_mfma_f32_16x16x32_bf16 v[60:63], v[204:207], v[188:191], v[60:63]
	s_waitcnt vmcnt(0)
	v_mfma_f32_16x16x32_bf16 v[0:3], v[80:83], v[64:67], v[0:3]
	v_mfma_f32_16x16x32_bf16 v[4:7], v[84:87], v[64:67], v[4:7]
	v_mfma_f32_16x16x32_bf16 v[8:11], v[88:91], v[64:67], v[8:11]
	v_mfma_f32_16x16x32_bf16 v[12:15], v[92:95], v[64:67], v[12:15]
	v_mfma_f32_16x16x32_bf16 v[16:19], v[80:83], v[68:71], v[16:19]
	v_mfma_f32_16x16x32_bf16 v[20:23], v[84:87], v[68:71], v[20:23]
	v_mfma_f32_16x16x32_bf16 v[24:27], v[88:91], v[68:71], v[24:27]
	v_mfma_f32_16x16x32_bf16 v[28:31], v[92:95], v[68:71], v[28:31]
	v_mfma_f32_16x16x32_bf16 v[32:35], v[80:83], v[72:75], v[32:35]
	v_mfma_f32_16x16x32_bf16 v[36:39], v[84:87], v[72:75], v[36:39]
	v_mfma_f32_16x16x32_bf16 v[40:43], v[88:91], v[72:75], v[40:43]
	v_mfma_f32_16x16x32_bf16 v[44:47], v[92:95], v[72:75], v[44:47]
	v_mfma_f32_16x16x32_bf16 v[48:51], v[80:83], v[76:79], v[48:51]
	v_mfma_f32_16x16x32_bf16 v[52:55], v[84:87], v[76:79], v[52:55]
	v_mfma_f32_16x16x32_bf16 v[56:59], v[88:91], v[76:79], v[56:59]
	v_mfma_f32_16x16x32_bf16 v[60:63], v[92:95], v[76:79], v[60:63]
	s_nop 7
	ds_write_b128 v136, v[0:3]
	ds_write_b128 v136, v[4:7] offset:8192
	ds_write_b128 v136, v[8:11] offset:16384
	ds_write_b128 v136, v[12:15] offset:24576
	ds_write_b128 v136, v[16:19] offset:32768
	ds_write_b128 v136, v[20:23] offset:40960
	ds_write_b128 v136, v[24:27] offset:49152
	ds_write_b128 v136, v[28:31] offset:57344
	ds_write_b128 v137, v[32:35]
	ds_write_b128 v137, v[36:39] offset:8192
	ds_write_b128 v137, v[40:43] offset:16384
	ds_write_b128 v137, v[44:47] offset:24576
	ds_write_b128 v137, v[48:51] offset:32768
	ds_write_b128 v137, v[52:55] offset:40960
	ds_write_b128 v137, v[56:59] offset:49152
	ds_write_b128 v137, v[60:63] offset:57344
	s_waitcnt lgkmcnt(0)
	s_barrier
	ds_read_b128 v[64:67], v138
	ds_read_b128 v[68:71], v138 offset:1024
	ds_read_b128 v[72:75], v138 offset:2048
	ds_read_b128 v[76:79], v138 offset:3072
	ds_read_b128 v[80:83], v138 offset:4096
	ds_read_b128 v[84:87], v138 offset:5120
	ds_read_b128 v[88:91], v138 offset:6144
	ds_read_b128 v[92:95], v138 offset:7168
	ds_read_b128 v[96:99], v138 offset:8192
	ds_read_b128 v[100:103], v138 offset:9216
	ds_read_b128 v[104:107], v138 offset:10240
	ds_read_b128 v[108:111], v138 offset:11264
	ds_read_b128 v[112:115], v138 offset:12288
	ds_read_b128 v[116:119], v138 offset:13312
	ds_read_b128 v[120:123], v138 offset:14336
	ds_read_b128 v[124:127], v138 offset:15360
	s_waitcnt lgkmcnt(0)
	v_pk_add_f32 v[64:65], v[64:65], v[68:69]
	v_pk_add_f32 v[66:67], v[66:67], v[70:71]
	v_pk_add_f32 v[96:97], v[96:97], v[100:101]
	v_pk_add_f32 v[98:99], v[98:99], v[102:103]
	v_pk_add_f32 v[64:65], v[64:65], v[72:73]
	v_pk_add_f32 v[66:67], v[66:67], v[74:75]
	v_pk_add_f32 v[96:97], v[96:97], v[104:105]
	v_pk_add_f32 v[98:99], v[98:99], v[106:107]
	v_pk_add_f32 v[64:65], v[64:65], v[76:77]
	v_pk_add_f32 v[66:67], v[66:67], v[78:79]
	v_pk_add_f32 v[96:97], v[96:97], v[108:109]
	v_pk_add_f32 v[98:99], v[98:99], v[110:111]
	v_pk_add_f32 v[64:65], v[64:65], v[80:81]
	v_pk_add_f32 v[66:67], v[66:67], v[82:83]
	v_pk_add_f32 v[96:97], v[96:97], v[112:113]
	v_pk_add_f32 v[98:99], v[98:99], v[114:115]
	v_pk_add_f32 v[64:65], v[64:65], v[84:85]
	v_pk_add_f32 v[66:67], v[66:67], v[86:87]
	v_pk_add_f32 v[96:97], v[96:97], v[116:117]
	v_pk_add_f32 v[98:99], v[98:99], v[118:119]
	v_pk_add_f32 v[64:65], v[64:65], v[88:89]
	v_pk_add_f32 v[66:67], v[66:67], v[90:91]
	v_pk_add_f32 v[96:97], v[96:97], v[120:121]
	v_pk_add_f32 v[98:99], v[98:99], v[122:123]
	v_pk_add_f32 v[64:65], v[64:65], v[92:93]
	v_pk_add_f32 v[66:67], v[66:67], v[94:95]
	v_pk_add_f32 v[96:97], v[96:97], v[124:125]
	v_pk_add_f32 v[98:99], v[98:99], v[126:127]
	s_waitcnt vmcnt(0)
	v_lshlrev_b32_e32 v140, 16, v209
	v_and_b32_e32 v141, 0xffff0000, v209
	v_and_b32_e32 v209, 0xffff0000, v208
	v_lshlrev_b32_e32 v208, 16, v208
	v_lshlrev_b32_e32 v142, 16, v211
	v_and_b32_e32 v143, 0xffff0000, v211
	v_and_b32_e32 v211, 0xffff0000, v210
	v_lshlrev_b32_e32 v210, 16, v210
	v_pk_fma_f32 v[64:65], v[208:209], s[12:13], v[64:65] op_sel_hi:[1,0,1]
	v_pk_fma_f32 v[66:67], v[140:141], s[12:13], v[66:67] op_sel_hi:[1,0,1]
	v_pk_fma_f32 v[96:97], v[210:211], s[12:13], v[96:97] op_sel_hi:[1,0,1]
	v_pk_fma_f32 v[98:99], v[142:143], s[12:13], v[98:99] op_sel_hi:[1,0,1]
	v_cvt_pk_bf16_f32 v64, v64, v65
	v_cvt_pk_bf16_f32 v65, v66, v67
	v_cvt_pk_bf16_f32 v96, v96, v97
	v_cvt_pk_bf16_f32 v97, v98, v99
	global_store_dwordx2 v139, v[64:65], s[10:11]
	global_store_dwordx2 v139, v[96:97], s[10:11] offset:32
	s_getreg_b32 s2, hwreg(HW_REG_XCC_ID, 0, 4)
	s_waitcnt vmcnt(0)
	v_mov_b32_e32 v0, v154
	s_waitcnt lgkmcnt(0)
	s_barrier
	s_nop 0
	v_cmp_eq_u32_e32 vcc, 0, v0
	s_and_saveexec_b64 s[0:1], vcc
	s_cbranch_execz .LBB0_629
	s_add_i32 s4, 0, 0x20010
	v_mov_b32_e32 v0, s4
	s_waitcnt vmcnt(0) expcnt(0) lgkmcnt(0)
	ds_read_b32 v2, v0
	s_add_i32 s4, 0, 0x20014
	v_mov_b32_e32 v0, s4
	ds_read_b32 v0, v0
	s_and_b32 s2, s2, 15
	s_waitcnt lgkmcnt(1)
	v_cmp_ne_u32_e32 vcc, 0, v2
	s_cbranch_vccnz .LBB0_593
	v_readlane_b32 s4, v255, 1
	s_mul_i32 s18, s85, s4
	s_add_u32 s4, s36, 0x1000
	s_addc_u32 s5, s37, 0
	s_add_u32 s6, s36, 0x1100
	s_addc_u32 s7, s37, 0
	s_add_u32 s8, s36, 0x1200
	s_addc_u32 s9, s37, 0
	s_add_u32 s10, s36, 0x1300
	s_mul_i32 s18, s18, s84
	s_addc_u32 s11, s37, 0
	s_mov_b32 s19, 1
	v_mov_b32_e32 v16, 0
	s_branch .LBB0_581

.LBB0_747:
	s_or_b64 exec, exec, s[0:1]
	s_mov_b64 s[4:5], s[36:37]
	s_mov_b64 s[0:1], s[94:95]
	s_waitcnt lgkmcnt(0)
	s_barrier
	v_readlane_b32 s2, v255, 36
	v_readlane_b32 s0, v255, 0
	s_add_i32 s0, s0, s84
	s_ashr_i32 s1, s0, 31
	s_abs_i32 s0, s0
	s_mul_hi_u32 s2, s0, s2
	s_mul_i32 s2, s2, s60
	s_sub_i32 s0, s0, s2
	s_sub_i32 s2, s0, s60
	s_cmp_ge_u32 s0, s60
	s_cselect_b32 s0, s2, s0
	s_sub_i32 s2, s0, s60
	s_cmp_ge_u32 s0, s60
	s_cselect_b32 s0, s2, s0
	s_xor_b32 s0, s0, s1
	s_sub_i32 s2, s0, s1
	s_cmpk_gt_i32 s2, 0x20f
	s_cbranch_scc1 .LBB0_758
	s_add_u32 s6, s4, 0x44c4000
	s_addc_u32 s7, s5, 0
	s_add_u32 s8, s4, 0x86c4000
	s_addc_u32 s9, s5, 0
	s_add_u32 s31, s4, 0xc8c4000
	s_addc_u32 s46, s5, 0
	s_add_u32 s47, s4, 0x29c4000
	s_addc_u32 s48, s5, 0
	s_ashr_i32 s49, s2, 31
	s_lshr_b32 s0, s49, 29
	s_add_i32 s0, s2, s0
	s_ashr_i32 s1, s0, 3
	s_and_b32 s0, s0, -8
	s_sub_i32 s0, s2, s0
	s_cmp_lt_i32 s0, 0
	s_movk_i32 s50, 0x43
	s_cselect_b32 s10, s50, 0x42
	s_mul_i32 s0, s10, s0
	s_add_i32 s0, s0, s1
	s_ashr_i32 s1, s0, 31
	s_lshr_b32 s1, s1, 27
	s_add_i32 s1, s0, s1
	s_ashr_i32 s10, s1, 5
	s_andn2_b32 s1, s1, 31
	s_lshl_b32 s10, s10, 3
	s_sub_i32 s11, s0, s1
	s_sub_i32 s0, 0x84, s10
	s_min_u32 s12, s0, 8
	v_cvt_f32_ubyte0_e32 v1, s12
	v_cvt_f32_i32_e32 v0, s11
	v_rcp_iflag_f32_e32 v2, v1
	s_ashr_i32 s0, s11, 30
	s_or_b32 s13, s0, 1
	s_mov_b32 s51, 0
	v_mul_f32_e32 v2, v0, v2
	v_trunc_f32_e32 v2, v2
	v_fma_f32 v0, -v2, v1, v0
	v_cvt_i32_f32_e32 v2, v2
	v_cmp_ge_f32_e64 s[0:1], |v0|, v1
	s_and_b64 s[0:1], s[0:1], exec
	s_cselect_b32 s0, s13, 0
	v_readfirstlane_b32 s1, v2
	s_add_i32 s0, s1, s0
	s_sext_i32_i8 s40, s0
	s_mul_i32 s0, s0, s12
	s_sub_i32 s0, s11, s0
	s_sext_i32_i8 s0, s0
	s_add_i32 s42, s10, s0
	v_mov_b64_e32 v[128:129], 0x1ff
	s_movk_i32 s52, 0x1600
	s_movk_i32 s53, 0xb00
	s_mov_b64 s[10:11], 0x80
	s_movk_i32 s54, 0x3c0
	s_mov_b64 s[12:13], 0xc974080
	s_mov_b64 s[14:15], 0x29c4100
	s_mov_b64 s[16:17], 0xc8c4100
	s_mov_b64 s[18:19], 0x2a74100
	s_mov_b64 s[20:21], 0xc974100
	s_mov_b64 s[22:23], 0x29c4180
	s_mov_b64 s[24:25], 0xc8c4180
	s_mov_b64 s[26:27], 0x2a74180
	s_mov_b64 s[28:29], 0x100
	s_movk_i32 s55, 0x100
	v_mov_b32_e32 v131, 0
	s_mov_b32 s30, 0x3fb504f3
	v_mov_b32_e32 v148, 1
	s_branch .LBB0_750

.Ltail2_gd:
	s_add_i32 s26, s26, s25
	s_lshr_b32 s25, s17, 2
	s_and_b32 s24, s17, 3
	s_lshl_b32 s26, s26, 8
	s_lshl_b32 s25, s25, 6
	s_add_i32 s26, s26, s25
	s_lshl_b32 s27, s27, 8
	s_lshl_b32 s24, s24, 6
	s_add_i32 s27, s27, s24
	s_add_u32 s4, s36, 0xc8c4000
	s_addc_u32 s5, s37, 0
	s_add_u32 s6, s36, 0x29c4000
	s_addc_u32 s7, s37, 0
	s_add_u32 s8, s36, 0x86c4000
	s_addc_u32 s9, s37, 0
	s_add_u32 s10, s36, 0x44c4000
	s_addc_u32 s11, s37, 0
	s_mov_b32 s12, 0x3fb504f3
	s_mov_b32 s13, 0
	s_mov_b32 s17, 0x1600
	v_and_b32_e32 v140, 63, v154
	v_lshrrev_b32_e32 v141, 6, v154
	v_and_b32_e32 v142, 15, v140
	v_lshrrev_b32_e32 v143, 4, v140
	v_mul_u32_u24_e32 v139, 0x2c0, v141
	v_lshl_add_u32 v139, v143, 4, v139
	v_add_u32_e32 v128, s26, v142
	v_mul_lo_u32 v128, v128, s17
	v_add_u32_e32 v128, v128, v139
	v_add_u32_e32 v129, 0x16000, v128
	v_add_u32_e32 v130, 0x2c000, v128
	v_add_u32_e32 v131, 0x42000, v128
	v_add_u32_e32 v132, s27, v142
	v_mul_lo_u32 v132, v132, s17
	v_add_u32_e32 v132, v132, v139
	v_add_u32_e32 v133, 0x16000, v132
	v_add_u32_e32 v134, 0x2c000, v132
	v_add_u32_e32 v135, 0x42000, v132
	v_lshrrev_b32_e32 v138, 1, v141
	v_lshl_add_u32 v138, v138, 4, v142
	v_add_u32_e32 v138, s26, v138
	v_lshlrev_b32_e32 v138, 11, v138
	v_and_b32_e32 v139, 1, v141
	v_lshlrev_b32_e32 v139, 6, v139
	v_lshl_add_u32 v139, v143, 3, v139
	s_lshl_b32 s16, s27, 1
	v_add3_u32 v139, v138, v139, s16
	global_load_dwordx2 v[212:213], v139, s[8:9]
	global_load_dwordx2 v[214:215], v139, s[8:9] offset:32
	v_lshlrev_b32_e32 v136, 4, v154
	v_add_u32_e32 v137, 0x10000, v136
	v_lshlrev_b32_e32 v138, 4, v140
	v_lshl_add_u32 v138, v141, 14, v138
	global_load_dwordx4 v[64:67], v128, s[4:5]
	global_load_dwordx4 v[68:71], v129, s[4:5]
	global_load_dwordx4 v[72:75], v130, s[4:5]
	global_load_dwordx4 v[76:79], v131, s[4:5]
	global_load_dwordx4 v[80:83], v132, s[6:7]
	global_load_dwordx4 v[84:87], v133, s[6:7]
	global_load_dwordx4 v[88:91], v134, s[6:7]
	global_load_dwordx4 v[92:95], v135, s[6:7]
	global_load_dwordx4 v[96:99], v128, s[4:5] offset:64
	global_load_dwordx4 v[100:103], v129, s[4:5] offset:64
	global_load_dwordx4 v[104:107], v130, s[4:5] offset:64
	global_load_dwordx4 v[108:111], v131, s[4:5] offset:64
	global_load_dwordx4 v[112:115], v132, s[6:7] offset:64
	global_load_dwordx4 v[116:119], v133, s[6:7] offset:64
	global_load_dwordx4 v[120:123], v134, s[6:7] offset:64
	global_load_dwordx4 v[124:127], v135, s[6:7] offset:64
	global_load_dwordx4 v[180:183], v128, s[4:5] offset:128
	global_load_dwordx4 v[184:187], v129, s[4:5] offset:128
	global_load_dwordx4 v[188:191], v130, s[4:5] offset:128
	global_load_dwordx4 v[192:195], v131, s[4:5] offset:128
	global_load_dwordx4 v[196:199], v132, s[6:7] offset:128
	global_load_dwordx4 v[200:203], v133, s[6:7] offset:128
	global_load_dwordx4 v[204:207], v134, s[6:7] offset:128
	global_load_dwordx4 v[208:211], v135, s[6:7] offset:128
	s_waitcnt vmcnt(16)
	v_mfma_f32_16x16x32_bf16 v[0:3], v[80:83], v[64:67], 0
	v_mfma_f32_16x16x32_bf16 v[4:7], v[84:87], v[64:67], 0
	v_mfma_f32_16x16x32_bf16 v[8:11], v[88:91], v[64:67], 0
	v_mfma_f32_16x16x32_bf16 v[12:15], v[92:95], v[64:67], 0
	v_mfma_f32_16x16x32_bf16 v[16:19], v[80:83], v[68:71], 0
	v_mfma_f32_16x16x32_bf16 v[20:23], v[84:87], v[68:71], 0
	v_mfma_f32_16x16x32_bf16 v[24:27], v[88:91], v[68:71], 0
	v_mfma_f32_16x16x32_bf16 v[28:31], v[92:95], v[68:71], 0
	v_mfma_f32_16x16x32_bf16 v[32:35], v[80:83], v[72:75], 0
	v_mfma_f32_16x16x32_bf16 v[36:39], v[84:87], v[72:75], 0
	v_mfma_f32_16x16x32_bf16 v[40:43], v[88:91], v[72:75], 0
	v_mfma_f32_16x16x32_bf16 v[44:47], v[92:95], v[72:75], 0
	v_mfma_f32_16x16x32_bf16 v[48:51], v[80:83], v[76:79], 0
	v_mfma_f32_16x16x32_bf16 v[52:55], v[84:87], v[76:79], 0
	v_mfma_f32_16x16x32_bf16 v[56:59], v[88:91], v[76:79], 0
	v_mfma_f32_16x16x32_bf16 v[60:63], v[92:95], v[76:79], 0
	global_load_dwordx4 v[64:67], v128, s[4:5] offset:192
	global_load_dwordx4 v[68:71], v129, s[4:5] offset:192
	global_load_dwordx4 v[72:75], v130, s[4:5] offset:192
	global_load_dwordx4 v[76:79], v131, s[4:5] offset:192
	global_load_dwordx4 v[80:83], v132, s[6:7] offset:192
	global_load_dwordx4 v[84:87], v133, s[6:7] offset:192
	global_load_dwordx4 v[88:91], v134, s[6:7] offset:192
	global_load_dwordx4 v[92:95], v135, s[6:7] offset:192
	s_waitcnt vmcnt(16)
	v_mfma_f32_16x16x32_bf16 v[0:3], v[112:115], v[96:99], v[0:3]
	v_mfma_f32_16x16x32_bf16 v[4:7], v[116:119], v[96:99], v[4:7]
	v_mfma_f32_16x16x32_bf16 v[8:11], v[120:123], v[96:99], v[8:11]
	v_mfma_f32_16x16x32_bf16 v[12:15], v[124:127], v[96:99], v[12:15]
	v_mfma_f32_16x16x32_bf16 v[16:19], v[112:115], v[100:103], v[16:19]
	v_mfma_f32_16x16x32_bf16 v[20:23], v[116:119], v[100:103], v[20:23]
	v_mfma_f32_16x16x32_bf16 v[24:27], v[120:123], v[100:103], v[24:27]
	v_mfma_f32_16x16x32_bf16 v[28:31], v[124:127], v[100:103], v[28:31]
	v_mfma_f32_16x16x32_bf16 v[32:35], v[112:115], v[104:107], v[32:35]
	v_mfma_f32_16x16x32_bf16 v[36:39], v[116:119], v[104:107], v[36:39]
	v_mfma_f32_16x16x32_bf16 v[40:43], v[120:123], v[104:107], v[40:43]
	v_mfma_f32_16x16x32_bf16 v[44:47], v[124:127], v[104:107], v[44:47]
	v_mfma_f32_16x16x32_bf16 v[48:51], v[112:115], v[108:111], v[48:51]
	v_mfma_f32_16x16x32_bf16 v[52:55], v[116:119], v[108:111], v[52:55]
	v_mfma_f32_16x16x32_bf16 v[56:59], v[120:123], v[108:111], v[56:59]
	v_mfma_f32_16x16x32_bf16 v[60:63], v[124:127], v[108:111], v[60:63]
	global_load_dwordx4 v[96:99], v128, s[4:5] offset:256
	global_load_dwordx4 v[100:103], v129, s[4:5] offset:256
	global_load_dwordx4 v[104:107], v130, s[4:5] offset:256
	global_load_dwordx4 v[108:111], v131, s[4:5] offset:256
	global_load_dwordx4 v[112:115], v132, s[6:7] offset:256
	global_load_dwordx4 v[116:119], v133, s[6:7] offset:256
	global_load_dwordx4 v[120:123], v134, s[6:7] offset:256
	global_load_dwordx4 v[124:127], v135, s[6:7] offset:256
	s_waitcnt vmcnt(16)
	v_mfma_f32_16x16x32_bf16 v[0:3], v[196:199], v[180:183], v[0:3]
	v_mfma_f32_16x16x32_bf16 v[4:7], v[200:203], v[180:183], v[4:7]
	v_mfma_f32_16x16x32_bf16 v[8:11], v[204:207], v[180:183], v[8:11]
	v_mfma_f32_16x16x32_bf16 v[12:15], v[208:211], v[180:183], v[12:15]
	v_mfma_f32_16x16x32_bf16 v[16:19], v[196:199], v[184:187], v[16:19]
	v_mfma_f32_16x16x32_bf16 v[20:23], v[200:203], v[184:187], v[20:23]
	v_mfma_f32_16x16x32_bf16 v[24:27], v[204:207], v[184:187], v[24:27]
	v_mfma_f32_16x16x32_bf16 v[28:31], v[208:211], v[184:187], v[28:31]
	v_mfma_f32_16x16x32_bf16 v[32:35], v[196:199], v[188:191], v[32:35]
	v_mfma_f32_16x16x32_bf16 v[36:39], v[200:203], v[188:191], v[36:39]
	v_mfma_f32_16x16x32_bf16 v[40:43], v[204:207], v[188:191], v[40:43]
	v_mfma_f32_16x16x32_bf16 v[44:47], v[208:211], v[188:191], v[44:47]
	v_mfma_f32_16x16x32_bf16 v[48:51], v[196:199], v[192:195], v[48:51]
	v_mfma_f32_16x16x32_bf16 v[52:55], v[200:203], v[192:195], v[52:55]
	v_mfma_f32_16x16x32_bf16 v[56:59], v[204:207], v[192:195], v[56:59]
	v_mfma_f32_16x16x32_bf16 v[60:63], v[208:211], v[192:195], v[60:63]
	global_load_dwordx4 v[180:183], v128, s[4:5] offset:320
	global_load_dwordx4 v[184:187], v129, s[4:5] offset:320
	global_load_dwordx4 v[188:191], v130, s[4:5] offset:320
	global_load_dwordx4 v[192:195], v131, s[4:5] offset:320
	global_load_dwordx4 v[196:199], v132, s[6:7] offset:320
	global_load_dwordx4 v[200:203], v133, s[6:7] offset:320
	global_load_dwordx4 v[204:207], v134, s[6:7] offset:320
	global_load_dwordx4 v[208:211], v135, s[6:7] offset:320
	s_waitcnt vmcnt(16)
	v_mfma_f32_16x16x32_bf16 v[0:3], v[80:83], v[64:67], v[0:3]
	v_mfma_f32_16x16x32_bf16 v[4:7], v[84:87], v[64:67], v[4:7]
	v_mfma_f32_16x16x32_bf16 v[8:11], v[88:91], v[64:67], v[8:11]
	v_mfma_f32_16x16x32_bf16 v[12:15], v[92:95], v[64:67], v[12:15]
	v_mfma_f32_16x16x32_bf16 v[16:19], v[80:83], v[68:71], v[16:19]
	v_mfma_f32_16x16x32_bf16 v[20:23], v[84:87], v[68:71], v[20:23]
	v_mfma_f32_16x16x32_bf16 v[24:27], v[88:91], v[68:71], v[24:27]
	v_mfma_f32_16x16x32_bf16 v[28:31], v[92:95], v[68:71], v[28:31]
	v_mfma_f32_16x16x32_bf16 v[32:35], v[80:83], v[72:75], v[32:35]
	v_mfma_f32_16x16x32_bf16 v[36:39], v[84:87], v[72:75], v[36:39]
	v_mfma_f32_16x16x32_bf16 v[40:43], v[88:91], v[72:75], v[40:43]
	v_mfma_f32_16x16x32_bf16 v[44:47], v[92:95], v[72:75], v[44:47]
	v_mfma_f32_16x16x32_bf16 v[48:51], v[80:83], v[76:79], v[48:51]
	v_mfma_f32_16x16x32_bf16 v[52:55], v[84:87], v[76:79], v[52:55]
	v_mfma_f32_16x16x32_bf16 v[56:59], v[88:91], v[76:79], v[56:59]
	v_mfma_f32_16x16x32_bf16 v[60:63], v[92:95], v[76:79], v[60:63]
	global_load_dwordx4 v[64:67], v128, s[4:5] offset:384
	global_load_dwordx4 v[68:71], v129, s[4:5] offset:384
	global_load_dwordx4 v[72:75], v130, s[4:5] offset:384
	global_load_dwordx4 v[76:79], v131, s[4:5] offset:384
	global_load_dwordx4 v[80:83], v132, s[6:7] offset:384
	global_load_dwordx4 v[84:87], v133, s[6:7] offset:384
	global_load_dwordx4 v[88:91], v134, s[6:7] offset:384
	global_load_dwordx4 v[92:95], v135, s[6:7] offset:384
	s_waitcnt vmcnt(16)
	v_mfma_f32_16x16x32_bf16 v[0:3], v[112:115], v[96:99], v[0:3]
	v_mfma_f32_16x16x32_bf16 v[4:7], v[116:119], v[96:99], v[4:7]
	v_mfma_f32_16x16x32_bf16 v[8:11], v[120:123], v[96:99], v[8:11]
	v_mfma_f32_16x16x32_bf16 v[12:15], v[124:127], v[96:99], v[12:15]
	v_mfma_f32_16x16x32_bf16 v[16:19], v[112:115], v[100:103], v[16:19]
	v_mfma_f32_16x16x32_bf16 v[20:23], v[116:119], v[100:103], v[20:23]
	v_mfma_f32_16x16x32_bf16 v[24:27], v[120:123], v[100:103], v[24:27]
	v_mfma_f32_16x16x32_bf16 v[28:31], v[124:127], v[100:103], v[28:31]
	v_mfma_f32_16x16x32_bf16 v[32:35], v[112:115], v[104:107], v[32:35]
	v_mfma_f32_16x16x32_bf16 v[36:39], v[116:119], v[104:107], v[36:39]
	v_mfma_f32_16x16x32_bf16 v[40:43], v[120:123], v[104:107], v[40:43]
	v_mfma_f32_16x16x32_bf16 v[44:47], v[124:127], v[104:107], v[44:47]
	v_mfma_f32_16x16x32_bf16 v[48:51], v[112:115], v[108:111], v[48:51]
	v_mfma_f32_16x16x32_bf16 v[52:55], v[116:119], v[108:111], v[52:55]
	v_mfma_f32_16x16x32_bf16 v[56:59], v[120:123], v[108:111], v[56:59]
	v_mfma_f32_16x16x32_bf16 v[60:63], v[124:127], v[108:111], v[60:63]
	global_load_dwordx4 v[96:99], v128, s[4:5] offset:448
	global_load_dwordx4 v[100:103], v129, s[4:5] offset:448
	global_load_dwordx4 v[104:107], v130, s[4:5] offset:448
	global_load_dwordx4 v[108:111], v131, s[4:5] offset:448
	global_load_dwordx4 v[112:115], v132, s[6:7] offset:448
	global_load_dwordx4 v[116:119], v133, s[6:7] offset:448
	global_load_dwordx4 v[120:123], v134, s[6:7] offset:448
	global_load_dwordx4 v[124:127], v135, s[6:7] offset:448
	s_waitcnt vmcnt(16)
	v_mfma_f32_16x16x32_bf16 v[0:3], v[196:199], v[180:183], v[0:3]
	v_mfma_f32_16x16x32_bf16 v[4:7], v[200:203], v[180:183], v[4:7]
	v_mfma_f32_16x16x32_bf16 v[8:11], v[204:207], v[180:183], v[8:11]
	v_mfma_f32_16x16x32_bf16 v[12:15], v[208:211], v[180:183], v[12:15]
	v_mfma_f32_16x16x32_bf16 v[16:19], v[196:199], v[184:187], v[16:19]
	v_mfma_f32_16x16x32_bf16 v[20:23], v[200:203], v[184:187], v[20:23]
	v_mfma_f32_16x16x32_bf16 v[24:27], v[204:207], v[184:187], v[24:27]
	v_mfma_f32_16x16x32_bf16 v[28:31], v[208:211], v[184:187], v[28:31]
	v_mfma_f32_16x16x32_bf16 v[32:35], v[196:199], v[188:191], v[32:35]
	v_mfma_f32_16x16x32_bf16 v[36:39], v[200:203], v[188:191], v[36:39]
	v_mfma_f32_16x16x32_bf16 v[40:43], v[204:207], v[188:191], v[40:43]
	v_mfma_f32_16x16x32_bf16 v[44:47], v[208:211], v[188:191], v[44:47]
	v_mfma_f32_16x16x32_bf16 v[48:51], v[196:199], v[192:195], v[48:51]
	v_mfma_f32_16x16x32_bf16 v[52:55], v[200:203], v[192:195], v[52:55]
	v_mfma_f32_16x16x32_bf16 v[56:59], v[204:207], v[192:195], v[56:59]
	v_mfma_f32_16x16x32_bf16 v[60:63], v[208:211], v[192:195], v[60:63]
	global_load_dwordx4 v[180:183], v128, s[4:5] offset:512
	global_load_dwordx4 v[184:187], v129, s[4:5] offset:512
	global_load_dwordx4 v[188:191], v130, s[4:5] offset:512
	global_load_dwordx4 v[192:195], v131, s[4:5] offset:512
	global_load_dwordx4 v[196:199], v132, s[6:7] offset:512
	global_load_dwordx4 v[200:203], v133, s[6:7] offset:512
	global_load_dwordx4 v[204:207], v134, s[6:7] offset:512
	global_load_dwordx4 v[208:211], v135, s[6:7] offset:512
	s_waitcnt vmcnt(16)
	v_mfma_f32_16x16x32_bf16 v[0:3], v[80:83], v[64:67], v[0:3]
	v_mfma_f32_16x16x32_bf16 v[4:7], v[84:87], v[64:67], v[4:7]
	v_mfma_f32_16x16x32_bf16 v[8:11], v[88:91], v[64:67], v[8:11]
	v_mfma_f32_16x16x32_bf16 v[12:15], v[92:95], v[64:67], v[12:15]
	v_mfma_f32_16x16x32_bf16 v[16:19], v[80:83], v[68:71], v[16:19]
	v_mfma_f32_16x16x32_bf16 v[20:23], v[84:87], v[68:71], v[20:23]
	v_mfma_f32_16x16x32_bf16 v[24:27], v[88:91], v[68:71], v[24:27]
	v_mfma_f32_16x16x32_bf16 v[28:31], v[92:95], v[68:71], v[28:31]
	v_mfma_f32_16x16x32_bf16 v[32:35], v[80:83], v[72:75], v[32:35]
	v_mfma_f32_16x16x32_bf16 v[36:39], v[84:87], v[72:75], v[36:39]
	v_mfma_f32_16x16x32_bf16 v[40:43], v[88:91], v[72:75], v[40:43]
	v_mfma_f32_16x16x32_bf16 v[44:47], v[92:95], v[72:75], v[44:47]
	v_mfma_f32_16x16x32_bf16 v[48:51], v[80:83], v[76:79], v[48:51]
	v_mfma_f32_16x16x32_bf16 v[52:55], v[84:87], v[76:79], v[52:55]
	v_mfma_f32_16x16x32_bf16 v[56:59], v[88:91], v[76:79], v[56:59]
	v_mfma_f32_16x16x32_bf16 v[60:63], v[92:95], v[76:79], v[60:63]
	global_load_dwordx4 v[64:67], v128, s[4:5] offset:576
	global_load_dwordx4 v[68:71], v129, s[4:5] offset:576
	global_load_dwordx4 v[72:75], v130, s[4:5] offset:576
	global_load_dwordx4 v[76:79], v131, s[4:5] offset:576
	global_load_dwordx4 v[80:83], v132, s[6:7] offset:576
	global_load_dwordx4 v[84:87], v133, s[6:7] offset:576
	global_load_dwordx4 v[88:91], v134, s[6:7] offset:576
	global_load_dwordx4 v[92:95], v135, s[6:7] offset:576
	s_waitcnt vmcnt(16)
	v_mfma_f32_16x16x32_bf16 v[0:3], v[112:115], v[96:99], v[0:3]
	v_mfma_f32_16x16x32_bf16 v[4:7], v[116:119], v[96:99], v[4:7]
	v_mfma_f32_16x16x32_bf16 v[8:11], v[120:123], v[96:99], v[8:11]
	v_mfma_f32_16x16x32_bf16 v[12:15], v[124:127], v[96:99], v[12:15]
	v_mfma_f32_16x16x32_bf16 v[16:19], v[112:115], v[100:103], v[16:19]
	v_mfma_f32_16x16x32_bf16 v[20:23], v[116:119], v[100:103], v[20:23]
	v_mfma_f32_16x16x32_bf16 v[24:27], v[120:123], v[100:103], v[24:27]
	v_mfma_f32_16x16x32_bf16 v[28:31], v[124:127], v[100:103], v[28:31]
	v_mfma_f32_16x16x32_bf16 v[32:35], v[112:115], v[104:107], v[32:35]
	v_mfma_f32_16x16x32_bf16 v[36:39], v[116:119], v[104:107], v[36:39]
	v_mfma_f32_16x16x32_bf16 v[40:43], v[120:123], v[104:107], v[40:43]
	v_mfma_f32_16x16x32_bf16 v[44:47], v[124:127], v[104:107], v[44:47]
	v_mfma_f32_16x16x32_bf16 v[48:51], v[112:115], v[108:111], v[48:51]
	v_mfma_f32_16x16x32_bf16 v[52:55], v[116:119], v[108:111], v[52:55]
	v_mfma_f32_16x16x32_bf16 v[56:59], v[120:123], v[108:111], v[56:59]
	v_mfma_f32_16x16x32_bf16 v[60:63], v[124:127], v[108:111], v[60:63]
	global_load_dwordx4 v[96:99], v128, s[4:5] offset:640
	global_load_dwordx4 v[100:103], v129, s[4:5] offset:640
	global_load_dwordx4 v[104:107], v130, s[4:5] offset:640
	global_load_dwordx4 v[108:111], v131, s[4:5] offset:640
	global_load_dwordx4 v[112:115], v132, s[6:7] offset:640
	global_load_dwordx4 v[116:119], v133, s[6:7] offset:640
	global_load_dwordx4 v[120:123], v134, s[6:7] offset:640
	global_load_dwordx4 v[124:127], v135, s[6:7] offset:640
	s_waitcnt vmcnt(16)
	v_mfma_f32_16x16x32_bf16 v[0:3], v[196:199], v[180:183], v[0:3]
	v_mfma_f32_16x16x32_bf16 v[4:7], v[200:203], v[180:183], v[4:7]
	v_mfma_f32_16x16x32_bf16 v[8:11], v[204:207], v[180:183], v[8:11]
	v_mfma_f32_16x16x32_bf16 v[12:15], v[208:211], v[180:183], v[12:15]
	v_mfma_f32_16x16x32_bf16 v[16:19], v[196:199], v[184:187], v[16:19]
	v_mfma_f32_16x16x32_bf16 v[20:23], v[200:203], v[184:187], v[20:23]
	v_mfma_f32_16x16x32_bf16 v[24:27], v[204:207], v[184:187], v[24:27]
	v_mfma_f32_16x16x32_bf16 v[28:31], v[208:211], v[184:187], v[28:31]
	v_mfma_f32_16x16x32_bf16 v[32:35], v[196:199], v[188:191], v[32:35]
	v_mfma_f32_16x16x32_bf16 v[36:39], v[200:203], v[188:191], v[36:39]
	v_mfma_f32_16x16x32_bf16 v[40:43], v[204:207], v[188:191], v[40:43]
	v_mfma_f32_16x16x32_bf16 v[44:47], v[208:211], v[188:191], v[44:47]
	v_mfma_f32_16x16x32_bf16 v[48:51], v[196:199], v[192:195], v[48:51]
	v_mfma_f32_16x16x32_bf16 v[52:55], v[200:203], v[192:195], v[52:55]
	v_mfma_f32_16x16x32_bf16 v[56:59], v[204:207], v[192:195], v[56:59]
	v_mfma_f32_16x16x32_bf16 v[60:63], v[208:211], v[192:195], v[60:63]
	s_waitcnt vmcnt(8)
	v_mfma_f32_16x16x32_bf16 v[0:3], v[80:83], v[64:67], v[0:3]
	v_mfma_f32_16x16x32_bf16 v[4:7], v[84:87], v[64:67], v[4:7]
	v_mfma_f32_16x16x32_bf16 v[8:11], v[88:91], v[64:67], v[8:11]
	v_mfma_f32_16x16x32_bf16 v[12:15], v[92:95], v[64:67], v[12:15]
	v_mfma_f32_16x16x32_bf16 v[16:19], v[80:83], v[68:71], v[16:19]
	v_mfma_f32_16x16x32_bf16 v[20:23], v[84:87], v[68:71], v[20:23]
	v_mfma_f32_16x16x32_bf16 v[24:27], v[88:91], v[68:71], v[24:27]
	v_mfma_f32_16x16x32_bf16 v[28:31], v[92:95], v[68:71], v[28:31]
	v_mfma_f32_16x16x32_bf16 v[32:35], v[80:83], v[72:75], v[32:35]
	v_mfma_f32_16x16x32_bf16 v[36:39], v[84:87], v[72:75], v[36:39]
	v_mfma_f32_16x16x32_bf16 v[40:43], v[88:91], v[72:75], v[40:43]
	v_mfma_f32_16x16x32_bf16 v[44:47], v[92:95], v[72:75], v[44:47]
	v_mfma_f32_16x16x32_bf16 v[48:51], v[80:83], v[76:79], v[48:51]
	v_mfma_f32_16x16x32_bf16 v[52:55], v[84:87], v[76:79], v[52:55]
	v_mfma_f32_16x16x32_bf16 v[56:59], v[88:91], v[76:79], v[56:59]
	v_mfma_f32_16x16x32_bf16 v[60:63], v[92:95], v[76:79], v[60:63]
	s_waitcnt vmcnt(0)
	v_mfma_f32_16x16x32_bf16 v[0:3], v[112:115], v[96:99], v[0:3]
	v_mfma_f32_16x16x32_bf16 v[4:7], v[116:119], v[96:99], v[4:7]
	v_mfma_f32_16x16x32_bf16 v[8:11], v[120:123], v[96:99], v[8:11]
	v_mfma_f32_16x16x32_bf16 v[12:15], v[124:127], v[96:99], v[12:15]
	v_mfma_f32_16x16x32_bf16 v[16:19], v[112:115], v[100:103], v[16:19]
	v_mfma_f32_16x16x32_bf16 v[20:23], v[116:119], v[100:103], v[20:23]
	v_mfma_f32_16x16x32_bf16 v[24:27], v[120:123], v[100:103], v[24:27]
	v_mfma_f32_16x16x32_bf16 v[28:31], v[124:127], v[100:103], v[28:31]
	v_mfma_f32_16x16x32_bf16 v[32:35], v[112:115], v[104:107], v[32:35]
	v_mfma_f32_16x16x32_bf16 v[36:39], v[116:119], v[104:107], v[36:39]
	v_mfma_f32_16x16x32_bf16 v[40:43], v[120:123], v[104:107], v[40:43]
	v_mfma_f32_16x16x32_bf16 v[44:47], v[124:127], v[104:107], v[44:47]
	v_mfma_f32_16x16x32_bf16 v[48:51], v[112:115], v[108:111], v[48:51]
	v_mfma_f32_16x16x32_bf16 v[52:55], v[116:119], v[108:111], v[52:55]
	v_mfma_f32_16x16x32_bf16 v[56:59], v[120:123], v[108:111], v[56:59]
	v_mfma_f32_16x16x32_bf16 v[60:63], v[124:127], v[108:111], v[60:63]
	s_nop 7
	ds_write_b128 v136, v[0:3]
	ds_write_b128 v136, v[4:7] offset:8192
	ds_write_b128 v136, v[8:11] offset:16384
	ds_write_b128 v136, v[12:15] offset:24576
	ds_write_b128 v136, v[16:19] offset:32768
	ds_write_b128 v136, v[20:23] offset:40960
	ds_write_b128 v136, v[24:27] offset:49152
	ds_write_b128 v136, v[28:31] offset:57344
	ds_write_b128 v137, v[32:35]
	ds_write_b128 v137, v[36:39] offset:8192
	ds_write_b128 v137, v[40:43] offset:16384
	ds_write_b128 v137, v[44:47] offset:24576
	ds_write_b128 v137, v[48:51] offset:32768
	ds_write_b128 v137, v[52:55] offset:40960
	ds_write_b128 v137, v[56:59] offset:49152
	ds_write_b128 v137, v[60:63] offset:57344
	s_waitcnt lgkmcnt(0)
	s_barrier
	ds_read_b128 v[64:67], v138
	ds_read_b128 v[68:71], v138 offset:1024
	ds_read_b128 v[72:75], v138 offset:2048
	ds_read_b128 v[76:79], v138 offset:3072
	ds_read_b128 v[80:83], v138 offset:4096
	ds_read_b128 v[84:87], v138 offset:5120
	ds_read_b128 v[88:91], v138 offset:6144
	ds_read_b128 v[92:95], v138 offset:7168
	ds_read_b128 v[96:99], v138 offset:8192
	ds_read_b128 v[100:103], v138 offset:9216
	ds_read_b128 v[104:107], v138 offset:10240
	ds_read_b128 v[108:111], v138 offset:11264
	ds_read_b128 v[112:115], v138 offset:12288
	ds_read_b128 v[116:119], v138 offset:13312
	ds_read_b128 v[120:123], v138 offset:14336
	ds_read_b128 v[124:127], v138 offset:15360
	s_waitcnt lgkmcnt(0)
	v_pk_add_f32 v[64:65], v[64:65], v[68:69]
	v_pk_add_f32 v[66:67], v[66:67], v[70:71]
	v_pk_add_f32 v[96:97], v[96:97], v[100:101]
	v_pk_add_f32 v[98:99], v[98:99], v[102:103]
	v_pk_add_f32 v[64:65], v[64:65], v[72:73]
	v_pk_add_f32 v[66:67], v[66:67], v[74:75]
	v_pk_add_f32 v[96:97], v[96:97], v[104:105]
	v_pk_add_f32 v[98:99], v[98:99], v[106:107]
	v_pk_add_f32 v[64:65], v[64:65], v[76:77]
	v_pk_add_f32 v[66:67], v[66:67], v[78:79]
	v_pk_add_f32 v[96:97], v[96:97], v[108:109]
	v_pk_add_f32 v[98:99], v[98:99], v[110:111]
	v_pk_add_f32 v[64:65], v[64:65], v[80:81]
	v_pk_add_f32 v[66:67], v[66:67], v[82:83]
	v_pk_add_f32 v[96:97], v[96:97], v[112:113]
	v_pk_add_f32 v[98:99], v[98:99], v[114:115]
	v_pk_add_f32 v[64:65], v[64:65], v[84:85]
	v_pk_add_f32 v[66:67], v[66:67], v[86:87]
	v_pk_add_f32 v[96:97], v[96:97], v[116:117]
	v_pk_add_f32 v[98:99], v[98:99], v[118:119]
	v_pk_add_f32 v[64:65], v[64:65], v[88:89]
	v_pk_add_f32 v[66:67], v[66:67], v[90:91]
	v_pk_add_f32 v[96:97], v[96:97], v[120:121]
	v_pk_add_f32 v[98:99], v[98:99], v[122:123]
	v_pk_add_f32 v[64:65], v[64:65], v[92:93]
	v_pk_add_f32 v[66:67], v[66:67], v[94:95]
	v_pk_add_f32 v[96:97], v[96:97], v[124:125]
	v_pk_add_f32 v[98:99], v[98:99], v[126:127]
	s_waitcnt vmcnt(0)
	v_lshlrev_b32_e32 v140, 16, v213
	v_and_b32_e32 v141, 0xffff0000, v213
	v_and_b32_e32 v213, 0xffff0000, v212
	v_lshlrev_b32_e32 v212, 16, v212
	v_lshlrev_b32_e32 v142, 16, v215
	v_and_b32_e32 v143, 0xffff0000, v215
	v_and_b32_e32 v215, 0xffff0000, v214
	v_lshlrev_b32_e32 v214, 16, v214
	v_pk_fma_f32 v[64:65], v[212:213], s[12:13], v[64:65] op_sel_hi:[1,0,1]
	v_pk_fma_f32 v[66:67], v[140:141], s[12:13], v[66:67] op_sel_hi:[1,0,1]
	v_pk_fma_f32 v[96:97], v[214:215], s[12:13], v[96:97] op_sel_hi:[1,0,1]
	v_pk_fma_f32 v[98:99], v[142:143], s[12:13], v[98:99] op_sel_hi:[1,0,1]
	v_cvt_pk_bf16_f32 v64, v64, v65
	v_cvt_pk_bf16_f32 v65, v66, v67
	v_cvt_pk_bf16_f32 v96, v96, v97
	v_cvt_pk_bf16_f32 v97, v98, v99
	global_store_dwordx2 v139, v[64:65], s[10:11]
	global_store_dwordx2 v139, v[96:97], s[10:11] offset:32
	s_getreg_b32 s2, hwreg(HW_REG_XCC_ID, 0, 4)
	s_waitcnt vmcnt(0)
	v_mov_b32_e32 v0, v154
	s_waitcnt lgkmcnt(0)
	s_barrier
	s_nop 0
	v_cmp_eq_u32_e32 vcc, 0, v0
	s_and_saveexec_b64 s[0:1], vcc
	s_cbranch_execz .LBB0_810
	s_add_i32 s4, 0, 0x20010
	v_mov_b32_e32 v0, s4
	s_waitcnt vmcnt(0) expcnt(0) lgkmcnt(0)
	ds_read_b32 v2, v0
	s_add_i32 s4, 0, 0x20014
	v_mov_b32_e32 v0, s4
	ds_read_b32 v0, v0
	s_and_b32 s2, s2, 15
	s_waitcnt lgkmcnt(1)
	v_cmp_ne_u32_e32 vcc, 0, v2
	s_cbranch_vccnz .LBB0_774
	v_readlane_b32 s4, v255, 1
	s_mul_i32 s18, s85, s4
	s_add_u32 s4, s36, 0x1000
	s_addc_u32 s5, s37, 0
	s_add_u32 s6, s36, 0x1100
	s_addc_u32 s7, s37, 0
	s_add_u32 s8, s36, 0x1200
	s_addc_u32 s9, s37, 0
	s_add_u32 s10, s36, 0x1300
	s_mul_i32 s18, s18, s84
	s_addc_u32 s11, s37, 0
	s_mov_b32 s19, 1
	v_mov_b32_e32 v16, 0
	s_branch .LBB0_762

.LBB0_1680:
	s_or_b64 exec, exec, s[0:1]
	s_mov_b64 s[4:5], s[36:37]
	s_mov_b64 s[0:1], s[94:95]
	s_waitcnt lgkmcnt(0)
	s_barrier
	v_readlane_b32 s2, v255, 36
	v_readlane_b32 s0, v255, 0
	s_add_i32 s0, s0, s84
	s_ashr_i32 s1, s0, 31
	s_abs_i32 s0, s0
	s_mul_hi_u32 s2, s0, s2
	s_mul_i32 s2, s2, s60
	s_sub_i32 s0, s0, s2
	s_sub_i32 s2, s0, s60
	s_cmp_ge_u32 s0, s60
	s_cselect_b32 s0, s2, s0
	s_sub_i32 s2, s0, s60
	s_cmp_ge_u32 s0, s60
	s_cselect_b32 s0, s2, s0
	s_xor_b32 s0, s0, s1
	s_sub_i32 s2, s0, s1
	s_cmpk_gt_i32 s2, 0x20f
	s_cbranch_scc1 .LBB0_1691
	s_add_u32 s6, s4, 0x44c4000
	s_addc_u32 s7, s5, 0
	s_add_u32 s39, s4, 0x86c4000
	s_addc_u32 s50, s5, 0
	s_add_u32 s8, s4, 0xc8c4000
	s_addc_u32 s9, s5, 0
	s_add_u32 s51, s4, 0x11c4000
	s_addc_u32 s52, s5, 0
	s_ashr_i32 s53, s2, 31
	s_lshr_b32 s0, s53, 29
	s_add_i32 s0, s2, s0
	s_ashr_i32 s1, s0, 3
	s_and_b32 s0, s0, -8
	s_sub_i32 s0, s2, s0
	s_cmp_lt_i32 s0, 0
	s_movk_i32 s54, 0x43
	s_cselect_b32 s10, s54, 0x42
	s_mul_i32 s0, s10, s0
	s_add_i32 s0, s0, s1
	s_ashr_i32 s1, s0, 31
	s_lshr_b32 s1, s1, 27
	s_add_i32 s1, s0, s1
	s_ashr_i32 s10, s1, 5
	s_andn2_b32 s1, s1, 31
	s_lshl_b32 s10, s10, 3
	s_sub_i32 s11, s0, s1
	s_sub_i32 s0, 0x84, s10
	s_min_u32 s12, s0, 8
	v_cvt_f32_ubyte0_e32 v1, s12
	v_cvt_f32_i32_e32 v0, s11
	v_rcp_iflag_f32_e32 v2, v1
	s_ashr_i32 s0, s11, 30
	s_or_b32 s13, s0, 1
	s_mov_b32 s55, 0
	v_mul_f32_e32 v2, v0, v2
	v_trunc_f32_e32 v2, v2
	v_fma_f32 v0, -v2, v1, v0
	v_cvt_i32_f32_e32 v2, v2
	v_cmp_ge_f32_e64 s[0:1], |v0|, v1
	s_and_b64 s[0:1], s[0:1], exec
	s_cselect_b32 s0, s13, 0
	v_readfirstlane_b32 s1, v2
	s_add_i32 s0, s1, s0
	s_sext_i32_i8 s43, s0
	s_mul_i32 s0, s0, s12
	s_sub_i32 s0, s11, s0
	s_sext_i32_i8 s0, s0
	s_add_i32 s42, s10, s0
	v_mov_b64_e32 v[128:129], 0x1ff
	s_mov_b64 s[10:11], 0x80
	s_movk_i32 s56, 0x3c0
	s_mov_b64 s[12:13], 0x8704080
	s_mov_b64 s[14:15], 0x11c4100
	s_mov_b64 s[16:17], 0x86c4100
	s_mov_b64 s[18:19], 0x1204100
	s_mov_b64 s[20:21], 0x8704100
	s_mov_b64 s[22:23], 0x11c4180
	s_mov_b64 s[24:25], 0x86c4180
	s_mov_b64 s[26:27], 0x1204180
	s_mov_b64 s[28:29], 0x100
	s_mov_b64 s[30:31], 0x780
	s_movk_i32 s57, 0x100
	v_mov_b32_e32 v131, 0
	s_mov_b32 s38, 0x3fb504f3
	v_mov_b32_e32 v144, 1
	s_branch .LBB0_1683

.Ltail3_gd:
	s_add_i32 s26, s26, s25
	s_lshr_b32 s25, s17, 2
	s_and_b32 s24, s17, 3
	s_lshl_b32 s26, s26, 8
	s_lshl_b32 s25, s25, 6
	s_add_i32 s26, s26, s25
	s_lshl_b32 s27, s27, 8
	s_lshl_b32 s24, s24, 6
	s_add_i32 s27, s27, s24
	s_add_u32 s4, s36, 0x86c4000
	s_addc_u32 s5, s37, 0
	s_add_u32 s6, s36, 0x11c4000
	s_addc_u32 s7, s37, 0
	s_add_u32 s8, s36, 0x44c4000
	s_addc_u32 s9, s37, 0
	s_add_u32 s10, s36, 0xc8c4000
	s_addc_u32 s11, s37, 0
	s_mov_b32 s12, 0x3fb504f3
	s_mov_b32 s13, 0
	s_mov_b32 s17, 0x800
	v_and_b32_e32 v140, 63, v154
	v_lshrrev_b32_e32 v141, 6, v154
	v_and_b32_e32 v142, 15, v140
	v_lshrrev_b32_e32 v143, 4, v140
	v_mul_u32_u24_e32 v139, 0x100, v141
	v_lshl_add_u32 v139, v143, 4, v139
	v_add_u32_e32 v128, s26, v142
	v_mul_lo_u32 v128, v128, s17
	v_add_u32_e32 v128, v128, v139
	v_add_u32_e32 v129, 0x8000, v128
	v_add_u32_e32 v130, 0x10000, v128
	v_add_u32_e32 v131, 0x18000, v128
	v_add_u32_e32 v132, s27, v142
	v_mul_lo_u32 v132, v132, s17
	v_add_u32_e32 v132, v132, v139
	v_add_u32_e32 v133, 0x8000, v132
	v_add_u32_e32 v134, 0x10000, v132
	v_add_u32_e32 v135, 0x18000, v132
	v_lshrrev_b32_e32 v138, 1, v141
	v_lshl_add_u32 v138, v138, 4, v142
	v_add_u32_e32 v138, s26, v138
	v_lshlrev_b32_e32 v138, 11, v138
	v_and_b32_e32 v139, 1, v141
	v_lshlrev_b32_e32 v139, 6, v139
	v_lshl_add_u32 v139, v143, 3, v139
	s_lshl_b32 s16, s27, 1
	v_add3_u32 v139, v138, v139, s16
	global_load_dwordx2 v[210:211], v139, s[8:9]
	global_load_dwordx2 v[212:213], v139, s[8:9] offset:32
	v_lshlrev_b32_e32 v136, 4, v154
	v_add_u32_e32 v137, 0x10000, v136
	v_lshlrev_b32_e32 v138, 4, v140
	v_lshl_add_u32 v138, v141, 14, v138
	global_load_dwordx4 v[64:67], v128, s[4:5]
	global_load_dwordx4 v[68:71], v129, s[4:5]
	global_load_dwordx4 v[72:75], v130, s[4:5]
	global_load_dwordx4 v[76:79], v131, s[4:5]
	global_load_dwordx4 v[80:83], v132, s[6:7]
	global_load_dwordx4 v[84:87], v133, s[6:7]
	global_load_dwordx4 v[88:91], v134, s[6:7]
	global_load_dwordx4 v[92:95], v135, s[6:7]
	global_load_dwordx4 v[96:99], v128, s[4:5] offset:64
	global_load_dwordx4 v[100:103], v129, s[4:5] offset:64
	global_load_dwordx4 v[104:107], v130, s[4:5] offset:64
	global_load_dwordx4 v[108:111], v131, s[4:5] offset:64
	global_load_dwordx4 v[112:115], v132, s[6:7] offset:64
	global_load_dwordx4 v[116:119], v133, s[6:7] offset:64
	global_load_dwordx4 v[120:123], v134, s[6:7] offset:64
	global_load_dwordx4 v[124:127], v135, s[6:7] offset:64
	global_load_dwordx4 v[178:181], v128, s[4:5] offset:128
	global_load_dwordx4 v[182:185], v129, s[4:5] offset:128
	global_load_dwordx4 v[186:189], v130, s[4:5] offset:128
	global_load_dwordx4 v[190:193], v131, s[4:5] offset:128
	global_load_dwordx4 v[194:197], v132, s[6:7] offset:128
	global_load_dwordx4 v[198:201], v133, s[6:7] offset:128
	global_load_dwordx4 v[202:205], v134, s[6:7] offset:128
	global_load_dwordx4 v[206:209], v135, s[6:7] offset:128
	s_waitcnt vmcnt(16)
	v_mfma_f32_16x16x32_bf16 v[0:3], v[80:83], v[64:67], 0
	v_mfma_f32_16x16x32_bf16 v[4:7], v[84:87], v[64:67], 0
	v_mfma_f32_16x16x32_bf16 v[8:11], v[88:91], v[64:67], 0
	v_mfma_f32_16x16x32_bf16 v[12:15], v[92:95], v[64:67], 0
	v_mfma_f32_16x16x32_bf16 v[16:19], v[80:83], v[68:71], 0
	v_mfma_f32_16x16x32_bf16 v[20:23], v[84:87], v[68:71], 0
	v_mfma_f32_16x16x32_bf16 v[24:27], v[88:91], v[68:71], 0
	v_mfma_f32_16x16x32_bf16 v[28:31], v[92:95], v[68:71], 0
	v_mfma_f32_16x16x32_bf16 v[32:35], v[80:83], v[72:75], 0
	v_mfma_f32_16x16x32_bf16 v[36:39], v[84:87], v[72:75], 0
	v_mfma_f32_16x16x32_bf16 v[40:43], v[88:91], v[72:75], 0
	v_mfma_f32_16x16x32_bf16 v[44:47], v[92:95], v[72:75], 0
	v_mfma_f32_16x16x32_bf16 v[48:51], v[80:83], v[76:79], 0
	v_mfma_f32_16x16x32_bf16 v[52:55], v[84:87], v[76:79], 0
	v_mfma_f32_16x16x32_bf16 v[56:59], v[88:91], v[76:79], 0
	v_mfma_f32_16x16x32_bf16 v[60:63], v[92:95], v[76:79], 0
	global_load_dwordx4 v[64:67], v128, s[4:5] offset:192
	global_load_dwordx4 v[68:71], v129, s[4:5] offset:192
	global_load_dwordx4 v[72:75], v130, s[4:5] offset:192
	global_load_dwordx4 v[76:79], v131, s[4:5] offset:192
	global_load_dwordx4 v[80:83], v132, s[6:7] offset:192
	global_load_dwordx4 v[84:87], v133, s[6:7] offset:192
	global_load_dwordx4 v[88:91], v134, s[6:7] offset:192
	global_load_dwordx4 v[92:95], v135, s[6:7] offset:192
	s_waitcnt vmcnt(16)
	v_mfma_f32_16x16x32_bf16 v[0:3], v[112:115], v[96:99], v[0:3]
	v_mfma_f32_16x16x32_bf16 v[4:7], v[116:119], v[96:99], v[4:7]
	v_mfma_f32_16x16x32_bf16 v[8:11], v[120:123], v[96:99], v[8:11]
	v_mfma_f32_16x16x32_bf16 v[12:15], v[124:127], v[96:99], v[12:15]
	v_mfma_f32_16x16x32_bf16 v[16:19], v[112:115], v[100:103], v[16:19]
	v_mfma_f32_16x16x32_bf16 v[20:23], v[116:119], v[100:103], v[20:23]
	v_mfma_f32_16x16x32_bf16 v[24:27], v[120:123], v[100:103], v[24:27]
	v_mfma_f32_16x16x32_bf16 v[28:31], v[124:127], v[100:103], v[28:31]
	v_mfma_f32_16x16x32_bf16 v[32:35], v[112:115], v[104:107], v[32:35]
	v_mfma_f32_16x16x32_bf16 v[36:39], v[116:119], v[104:107], v[36:39]
	v_mfma_f32_16x16x32_bf16 v[40:43], v[120:123], v[104:107], v[40:43]
	v_mfma_f32_16x16x32_bf16 v[44:47], v[124:127], v[104:107], v[44:47]
	v_mfma_f32_16x16x32_bf16 v[48:51], v[112:115], v[108:111], v[48:51]
	v_mfma_f32_16x16x32_bf16 v[52:55], v[116:119], v[108:111], v[52:55]
	v_mfma_f32_16x16x32_bf16 v[56:59], v[120:123], v[108:111], v[56:59]
	v_mfma_f32_16x16x32_bf16 v[60:63], v[124:127], v[108:111], v[60:63]
	s_waitcnt vmcnt(8)
	v_mfma_f32_16x16x32_bf16 v[0:3], v[194:197], v[178:181], v[0:3]
	v_mfma_f32_16x16x32_bf16 v[4:7], v[198:201], v[178:181], v[4:7]
	v_mfma_f32_16x16x32_bf16 v[8:11], v[202:205], v[178:181], v[8:11]
	v_mfma_f32_16x16x32_bf16 v[12:15], v[206:209], v[178:181], v[12:15]
	v_mfma_f32_16x16x32_bf16 v[16:19], v[194:197], v[182:185], v[16:19]
	v_mfma_f32_16x16x32_bf16 v[20:23], v[198:201], v[182:185], v[20:23]
	v_mfma_f32_16x16x32_bf16 v[24:27], v[202:205], v[182:185], v[24:27]
	v_mfma_f32_16x16x32_bf16 v[28:31], v[206:209], v[182:185], v[28:31]
	v_mfma_f32_16x16x32_bf16 v[32:35], v[194:197], v[186:189], v[32:35]
	v_mfma_f32_16x16x32_bf16 v[36:39], v[198:201], v[186:189], v[36:39]
	v_mfma_f32_16x16x32_bf16 v[40:43], v[202:205], v[186:189], v[40:43]
	v_mfma_f32_16x16x32_bf16 v[44:47], v[206:209], v[186:189], v[44:47]
	v_mfma_f32_16x16x32_bf16 v[48:51], v[194:197], v[190:193], v[48:51]
	v_mfma_f32_16x16x32_bf16 v[52:55], v[198:201], v[190:193], v[52:55]
	v_mfma_f32_16x16x32_bf16 v[56:59], v[202:205], v[190:193], v[56:59]
	v_mfma_f32_16x16x32_bf16 v[60:63], v[206:209], v[190:193], v[60:63]
	s_waitcnt vmcnt(0)
	v_mfma_f32_16x16x32_bf16 v[0:3], v[80:83], v[64:67], v[0:3]
	v_mfma_f32_16x16x32_bf16 v[4:7], v[84:87], v[64:67], v[4:7]
	v_mfma_f32_16x16x32_bf16 v[8:11], v[88:91], v[64:67], v[8:11]
	v_mfma_f32_16x16x32_bf16 v[12:15], v[92:95], v[64:67], v[12:15]
	v_mfma_f32_16x16x32_bf16 v[16:19], v[80:83], v[68:71], v[16:19]
	v_mfma_f32_16x16x32_bf16 v[20:23], v[84:87], v[68:71], v[20:23]
	v_mfma_f32_16x16x32_bf16 v[24:27], v[88:91], v[68:71], v[24:27]
	v_mfma_f32_16x16x32_bf16 v[28:31], v[92:95], v[68:71], v[28:31]
	v_mfma_f32_16x16x32_bf16 v[32:35], v[80:83], v[72:75], v[32:35]
	v_mfma_f32_16x16x32_bf16 v[36:39], v[84:87], v[72:75], v[36:39]
	v_mfma_f32_16x16x32_bf16 v[40:43], v[88:91], v[72:75], v[40:43]
	v_mfma_f32_16x16x32_bf16 v[44:47], v[92:95], v[72:75], v[44:47]
	v_mfma_f32_16x16x32_bf16 v[48:51], v[80:83], v[76:79], v[48:51]
	v_mfma_f32_16x16x32_bf16 v[52:55], v[84:87], v[76:79], v[52:55]
	v_mfma_f32_16x16x32_bf16 v[56:59], v[88:91], v[76:79], v[56:59]
	v_mfma_f32_16x16x32_bf16 v[60:63], v[92:95], v[76:79], v[60:63]
	s_nop 7
	ds_write_b128 v136, v[0:3]
	ds_write_b128 v136, v[4:7] offset:8192
	ds_write_b128 v136, v[8:11] offset:16384
	ds_write_b128 v136, v[12:15] offset:24576
	ds_write_b128 v136, v[16:19] offset:32768
	ds_write_b128 v136, v[20:23] offset:40960
	ds_write_b128 v136, v[24:27] offset:49152
	ds_write_b128 v136, v[28:31] offset:57344
	ds_write_b128 v137, v[32:35]
	ds_write_b128 v137, v[36:39] offset:8192
	ds_write_b128 v137, v[40:43] offset:16384
	ds_write_b128 v137, v[44:47] offset:24576
	ds_write_b128 v137, v[48:51] offset:32768
	ds_write_b128 v137, v[52:55] offset:40960
	ds_write_b128 v137, v[56:59] offset:49152
	ds_write_b128 v137, v[60:63] offset:57344
	s_waitcnt lgkmcnt(0)
	s_barrier
	ds_read_b128 v[64:67], v138
	ds_read_b128 v[68:71], v138 offset:1024
	ds_read_b128 v[72:75], v138 offset:2048
	ds_read_b128 v[76:79], v138 offset:3072
	ds_read_b128 v[80:83], v138 offset:4096
	ds_read_b128 v[84:87], v138 offset:5120
	ds_read_b128 v[88:91], v138 offset:6144
	ds_read_b128 v[92:95], v138 offset:7168
	ds_read_b128 v[96:99], v138 offset:8192
	ds_read_b128 v[100:103], v138 offset:9216
	ds_read_b128 v[104:107], v138 offset:10240
	ds_read_b128 v[108:111], v138 offset:11264
	ds_read_b128 v[112:115], v138 offset:12288
	ds_read_b128 v[116:119], v138 offset:13312
	ds_read_b128 v[120:123], v138 offset:14336
	ds_read_b128 v[124:127], v138 offset:15360
	s_waitcnt lgkmcnt(0)
	v_pk_add_f32 v[64:65], v[64:65], v[68:69]
	v_pk_add_f32 v[66:67], v[66:67], v[70:71]
	v_pk_add_f32 v[96:97], v[96:97], v[100:101]
	v_pk_add_f32 v[98:99], v[98:99], v[102:103]
	v_pk_add_f32 v[64:65], v[64:65], v[72:73]
	v_pk_add_f32 v[66:67], v[66:67], v[74:75]
	v_pk_add_f32 v[96:97], v[96:97], v[104:105]
	v_pk_add_f32 v[98:99], v[98:99], v[106:107]
	v_pk_add_f32 v[64:65], v[64:65], v[76:77]
	v_pk_add_f32 v[66:67], v[66:67], v[78:79]
	v_pk_add_f32 v[96:97], v[96:97], v[108:109]
	v_pk_add_f32 v[98:99], v[98:99], v[110:111]
	v_pk_add_f32 v[64:65], v[64:65], v[80:81]
	v_pk_add_f32 v[66:67], v[66:67], v[82:83]
	v_pk_add_f32 v[96:97], v[96:97], v[112:113]
	v_pk_add_f32 v[98:99], v[98:99], v[114:115]
	v_pk_add_f32 v[64:65], v[64:65], v[84:85]
	v_pk_add_f32 v[66:67], v[66:67], v[86:87]
	v_pk_add_f32 v[96:97], v[96:97], v[116:117]
	v_pk_add_f32 v[98:99], v[98:99], v[118:119]
	v_pk_add_f32 v[64:65], v[64:65], v[88:89]
	v_pk_add_f32 v[66:67], v[66:67], v[90:91]
	v_pk_add_f32 v[96:97], v[96:97], v[120:121]
	v_pk_add_f32 v[98:99], v[98:99], v[122:123]
	v_pk_add_f32 v[64:65], v[64:65], v[92:93]
	v_pk_add_f32 v[66:67], v[66:67], v[94:95]
	v_pk_add_f32 v[96:97], v[96:97], v[124:125]
	v_pk_add_f32 v[98:99], v[98:99], v[126:127]
	s_waitcnt vmcnt(0)
	v_lshlrev_b32_e32 v140, 16, v211
	v_and_b32_e32 v141, 0xffff0000, v211
	v_and_b32_e32 v211, 0xffff0000, v210
	v_lshlrev_b32_e32 v210, 16, v210
	v_lshlrev_b32_e32 v142, 16, v213
	v_and_b32_e32 v143, 0xffff0000, v213
	v_and_b32_e32 v213, 0xffff0000, v212
	v_lshlrev_b32_e32 v212, 16, v212
	v_pk_fma_f32 v[64:65], v[210:211], s[12:13], v[64:65] op_sel_hi:[1,0,1]
	v_pk_fma_f32 v[66:67], v[140:141], s[12:13], v[66:67] op_sel_hi:[1,0,1]
	v_pk_fma_f32 v[96:97], v[212:213], s[12:13], v[96:97] op_sel_hi:[1,0,1]
	v_pk_fma_f32 v[98:99], v[142:143], s[12:13], v[98:99] op_sel_hi:[1,0,1]
	v_cvt_pk_bf16_f32 v64, v64, v65
	v_cvt_pk_bf16_f32 v65, v66, v67
	v_cvt_pk_bf16_f32 v96, v96, v97
	v_cvt_pk_bf16_f32 v97, v98, v99
	global_store_dwordx2 v139, v[64:65], s[10:11]
	global_store_dwordx2 v139, v[96:97], s[10:11] offset:32
	s_getreg_b32 s2, hwreg(HW_REG_XCC_ID, 0, 4)
	s_waitcnt vmcnt(0)
	v_mov_b32_e32 v0, v154
	s_waitcnt lgkmcnt(0)
	s_barrier
	s_nop 0
	v_cmp_eq_u32_e32 vcc, 0, v0
	s_and_saveexec_b64 s[0:1], vcc
	s_cbranch_execz .LBB0_1743
	s_add_i32 s4, 0, 0x20010
	v_mov_b32_e32 v0, s4
	s_waitcnt vmcnt(0) expcnt(0) lgkmcnt(0)
	ds_read_b32 v2, v0
	s_add_i32 s4, 0, 0x20014
	v_mov_b32_e32 v0, s4
	ds_read_b32 v0, v0
	s_and_b32 s2, s2, 15
	s_waitcnt lgkmcnt(1)
	v_cmp_ne_u32_e32 vcc, 0, v2
	s_cbranch_vccnz .LBB0_1707
	v_readlane_b32 s4, v255, 1
	s_mul_i32 s18, s85, s4
	s_add_u32 s4, s36, 0x1000
	s_addc_u32 s5, s37, 0
	s_add_u32 s6, s36, 0x1100
	s_addc_u32 s7, s37, 0
	s_add_u32 s8, s36, 0x1200
	s_addc_u32 s9, s37, 0
	s_add_u32 s10, s36, 0x1300
	s_mul_i32 s18, s18, s84
	s_addc_u32 s11, s37, 0
	s_mov_b32 s19, 1
	v_mov_b32_e32 v16, 0
	s_branch .LBB0_1695

.LBB0_1864:
	s_add_i32 s51, s51, 1
	s_mul_i32 s0, s51, s35
	s_mul_hi_u32 s1, s51, s34
	s_add_i32 s1, s1, s0
	s_mul_i32 s0, s51, s34
	s_add_u32 s38, s0, s2
	s_addc_u32 s39, s1, s49
	v_mov_b64_e32 v[0:1], 0x1ff
	v_cmp_gt_i64_e64 s[0:1], s[38:39], v[0:1]
	s_and_b64 vcc, exec, s[0:1]
	s_mov_b32 s57, 0
	s_mov_b32 s56, 0
	s_cbranch_vccnz .LBB0_1866
	s_ashr_i32 s39, s38, 31
	s_lshr_b32 s39, s39, 29
	s_add_i32 s39, s38, s39
	s_ashr_i32 s41, s39, 3
	s_and_b32 s39, s39, -8
	s_sub_i32 s38, s38, s39
	s_cmp_lt_i32 s38, 0
	s_cselect_b32 s39, s50, 0x42
	s_mul_i32 s38, s39, s38
	s_add_i32 s38, s38, s41
	s_ashr_i32 s39, s38, 31
	s_lshr_b32 s39, s39, 27
	s_add_i32 s39, s38, s39
	s_ashr_i32 s41, s39, 5
	s_lshl_b32 s41, s41, 3
	s_sub_i32 s43, 0x84, s41
	s_min_i32 s43, s43, 8
	s_abs_i32 s44, s43
	v_cvt_f32_u32_e32 v0, s44
	s_sub_i32 s56, 0, s44
	s_andn2_b32 s39, s39, 31
	s_sub_i32 s38, s38, s39
	v_rcp_iflag_f32_e32 v0, v0
	s_abs_i32 s39, s38
	s_xor_b32 s45, s38, s43
	s_ashr_i32 s45, s45, 31
	v_mul_f32_e32 v0, 0x4f7ffffe, v0
	v_cvt_u32_f32_e32 v0, v0
	s_nop 0
	v_readfirstlane_b32 s57, v0
	s_mul_i32 s56, s56, s57
	s_mul_hi_u32 s56, s57, s56
	s_add_i32 s57, s57, s56
	s_mul_hi_u32 s56, s39, s57
	s_mul_i32 s57, s56, s44
	s_sub_i32 s39, s39, s57
	s_add_i32 s60, s56, 1
	s_sub_i32 s57, s39, s44
	s_cmp_ge_u32 s39, s44
	s_cselect_b32 s56, s60, s56
	s_cselect_b32 s39, s57, s39
	s_add_i32 s57, s56, 1
	s_cmp_ge_u32 s39, s44
	s_cselect_b32 s39, s57, s56
	s_xor_b32 s39, s39, s45
	s_sub_i32 s56, s39, s45
	s_mul_i32 s39, s56, s43
	s_sub_i32 s38, s38, s39
	s_add_i32 s57, s38, s41

.Ltail4_gd:
	s_add_i32 s26, s26, s25
	s_lshr_b32 s25, s17, 2
	s_and_b32 s24, s17, 3
	s_lshl_b32 s26, s26, 8
	s_lshl_b32 s25, s25, 6
	s_add_i32 s26, s26, s25
	s_lshl_b32 s27, s27, 8
	s_lshl_b32 s24, s24, 6
	s_add_i32 s27, s27, s24
	s_add_u32 s4, s36, 0xc8c4000
	s_addc_u32 s5, s37, 0
	s_add_u32 s6, s36, 0x2f44000
	s_addc_u32 s7, s37, 0
	s_add_u32 s8, s36, 0x86c4000
	s_addc_u32 s9, s37, 0
	s_add_u32 s10, s36, 0x44c4000
	s_addc_u32 s11, s37, 0
	s_mov_b32 s12, 0x3fb504f3
	s_mov_b32 s13, 0
	s_mov_b32 s17, 0x1600
	v_and_b32_e32 v140, 63, v154
	v_lshrrev_b32_e32 v141, 6, v154
	v_and_b32_e32 v142, 15, v140
	v_lshrrev_b32_e32 v143, 4, v140
	v_mul_u32_u24_e32 v139, 0x2c0, v141
	v_lshl_add_u32 v139, v143, 4, v139
	v_add_u32_e32 v128, s26, v142
	v_mul_lo_u32 v128, v128, s17
	v_add_u32_e32 v128, v128, v139
	v_add_u32_e32 v129, 0x16000, v128
	v_add_u32_e32 v130, 0x2c000, v128
	v_add_u32_e32 v131, 0x42000, v128
	v_add_u32_e32 v132, s27, v142
	v_mul_lo_u32 v132, v132, s17
	v_add_u32_e32 v132, v132, v139
	v_add_u32_e32 v133, 0x16000, v132
	v_add_u32_e32 v134, 0x2c000, v132
	v_add_u32_e32 v135, 0x42000, v132
	v_lshrrev_b32_e32 v138, 1, v141
	v_lshl_add_u32 v138, v138, 4, v142
	v_add_u32_e32 v138, s26, v138
	v_lshlrev_b32_e32 v138, 11, v138
	v_and_b32_e32 v139, 1, v141
	v_lshlrev_b32_e32 v139, 6, v139
	v_lshl_add_u32 v139, v143, 3, v139
	s_lshl_b32 s16, s27, 1
	v_add3_u32 v139, v138, v139, s16
	global_load_dwordx2 v[212:213], v139, s[8:9]
	global_load_dwordx2 v[214:215], v139, s[8:9] offset:32
	v_lshlrev_b32_e32 v136, 4, v154
	v_add_u32_e32 v137, 0x10000, v136
	v_lshlrev_b32_e32 v138, 4, v140
	v_lshl_add_u32 v138, v141, 14, v138
	global_load_dwordx4 v[64:67], v128, s[4:5]
	global_load_dwordx4 v[68:71], v129, s[4:5]
	global_load_dwordx4 v[72:75], v130, s[4:5]
	global_load_dwordx4 v[76:79], v131, s[4:5]
	global_load_dwordx4 v[80:83], v132, s[6:7]
	global_load_dwordx4 v[84:87], v133, s[6:7]
	global_load_dwordx4 v[88:91], v134, s[6:7]
	global_load_dwordx4 v[92:95], v135, s[6:7]
	global_load_dwordx4 v[96:99], v128, s[4:5] offset:64
	global_load_dwordx4 v[100:103], v129, s[4:5] offset:64
	global_load_dwordx4 v[104:107], v130, s[4:5] offset:64
	global_load_dwordx4 v[108:111], v131, s[4:5] offset:64
	global_load_dwordx4 v[112:115], v132, s[6:7] offset:64
	global_load_dwordx4 v[116:119], v133, s[6:7] offset:64
	global_load_dwordx4 v[120:123], v134, s[6:7] offset:64
	global_load_dwordx4 v[124:127], v135, s[6:7] offset:64
	global_load_dwordx4 v[180:183], v128, s[4:5] offset:128
	global_load_dwordx4 v[184:187], v129, s[4:5] offset:128
	global_load_dwordx4 v[188:191], v130, s[4:5] offset:128
	global_load_dwordx4 v[192:195], v131, s[4:5] offset:128
	global_load_dwordx4 v[196:199], v132, s[6:7] offset:128
	global_load_dwordx4 v[200:203], v133, s[6:7] offset:128
	global_load_dwordx4 v[204:207], v134, s[6:7] offset:128
	global_load_dwordx4 v[208:211], v135, s[6:7] offset:128
	s_waitcnt vmcnt(16)
	v_mfma_f32_16x16x32_bf16 v[0:3], v[80:83], v[64:67], 0
	v_mfma_f32_16x16x32_bf16 v[4:7], v[84:87], v[64:67], 0
	v_mfma_f32_16x16x32_bf16 v[8:11], v[88:91], v[64:67], 0
	v_mfma_f32_16x16x32_bf16 v[12:15], v[92:95], v[64:67], 0
	v_mfma_f32_16x16x32_bf16 v[16:19], v[80:83], v[68:71], 0
	v_mfma_f32_16x16x32_bf16 v[20:23], v[84:87], v[68:71], 0
	v_mfma_f32_16x16x32_bf16 v[24:27], v[88:91], v[68:71], 0
	v_mfma_f32_16x16x32_bf16 v[28:31], v[92:95], v[68:71], 0
	v_mfma_f32_16x16x32_bf16 v[32:35], v[80:83], v[72:75], 0
	v_mfma_f32_16x16x32_bf16 v[36:39], v[84:87], v[72:75], 0
	v_mfma_f32_16x16x32_bf16 v[40:43], v[88:91], v[72:75], 0
	v_mfma_f32_16x16x32_bf16 v[44:47], v[92:95], v[72:75], 0
	v_mfma_f32_16x16x32_bf16 v[48:51], v[80:83], v[76:79], 0
	v_mfma_f32_16x16x32_bf16 v[52:55], v[84:87], v[76:79], 0
	v_mfma_f32_16x16x32_bf16 v[56:59], v[88:91], v[76:79], 0
	v_mfma_f32_16x16x32_bf16 v[60:63], v[92:95], v[76:79], 0
	global_load_dwordx4 v[64:67], v128, s[4:5] offset:192
	global_load_dwordx4 v[68:71], v129, s[4:5] offset:192
	global_load_dwordx4 v[72:75], v130, s[4:5] offset:192
	global_load_dwordx4 v[76:79], v131, s[4:5] offset:192
	global_load_dwordx4 v[80:83], v132, s[6:7] offset:192
	global_load_dwordx4 v[84:87], v133, s[6:7] offset:192
	global_load_dwordx4 v[88:91], v134, s[6:7] offset:192
	global_load_dwordx4 v[92:95], v135, s[6:7] offset:192
	s_waitcnt vmcnt(16)
	v_mfma_f32_16x16x32_bf16 v[0:3], v[112:115], v[96:99], v[0:3]
	v_mfma_f32_16x16x32_bf16 v[4:7], v[116:119], v[96:99], v[4:7]
	v_mfma_f32_16x16x32_bf16 v[8:11], v[120:123], v[96:99], v[8:11]
	v_mfma_f32_16x16x32_bf16 v[12:15], v[124:127], v[96:99], v[12:15]
	v_mfma_f32_16x16x32_bf16 v[16:19], v[112:115], v[100:103], v[16:19]
	v_mfma_f32_16x16x32_bf16 v[20:23], v[116:119], v[100:103], v[20:23]
	v_mfma_f32_16x16x32_bf16 v[24:27], v[120:123], v[100:103], v[24:27]
	v_mfma_f32_16x16x32_bf16 v[28:31], v[124:127], v[100:103], v[28:31]
	v_mfma_f32_16x16x32_bf16 v[32:35], v[112:115], v[104:107], v[32:35]
	v_mfma_f32_16x16x32_bf16 v[36:39], v[116:119], v[104:107], v[36:39]
	v_mfma_f32_16x16x32_bf16 v[40:43], v[120:123], v[104:107], v[40:43]
	v_mfma_f32_16x16x32_bf16 v[44:47], v[124:127], v[104:107], v[44:47]
	v_mfma_f32_16x16x32_bf16 v[48:51], v[112:115], v[108:111], v[48:51]
	v_mfma_f32_16x16x32_bf16 v[52:55], v[116:119], v[108:111], v[52:55]
	v_mfma_f32_16x16x32_bf16 v[56:59], v[120:123], v[108:111], v[56:59]
	v_mfma_f32_16x16x32_bf16 v[60:63], v[124:127], v[108:111], v[60:63]
	global_load_dwordx4 v[96:99], v128, s[4:5] offset:256
	global_load_dwordx4 v[100:103], v129, s[4:5] offset:256
	global_load_dwordx4 v[104:107], v130, s[4:5] offset:256
	global_load_dwordx4 v[108:111], v131, s[4:5] offset:256
	global_load_dwordx4 v[112:115], v132, s[6:7] offset:256
	global_load_dwordx4 v[116:119], v133, s[6:7] offset:256
	global_load_dwordx4 v[120:123], v134, s[6:7] offset:256
	global_load_dwordx4 v[124:127], v135, s[6:7] offset:256
	s_waitcnt vmcnt(16)
	v_mfma_f32_16x16x32_bf16 v[0:3], v[196:199], v[180:183], v[0:3]
	v_mfma_f32_16x16x32_bf16 v[4:7], v[200:203], v[180:183], v[4:7]
	v_mfma_f32_16x16x32_bf16 v[8:11], v[204:207], v[180:183], v[8:11]
	v_mfma_f32_16x16x32_bf16 v[12:15], v[208:211], v[180:183], v[12:15]
	v_mfma_f32_16x16x32_bf16 v[16:19], v[196:199], v[184:187], v[16:19]
	v_mfma_f32_16x16x32_bf16 v[20:23], v[200:203], v[184:187], v[20:23]
	v_mfma_f32_16x16x32_bf16 v[24:27], v[204:207], v[184:187], v[24:27]
	v_mfma_f32_16x16x32_bf16 v[28:31], v[208:211], v[184:187], v[28:31]
	v_mfma_f32_16x16x32_bf16 v[32:35], v[196:199], v[188:191], v[32:35]
	v_mfma_f32_16x16x32_bf16 v[36:39], v[200:203], v[188:191], v[36:39]
	v_mfma_f32_16x16x32_bf16 v[40:43], v[204:207], v[188:191], v[40:43]
	v_mfma_f32_16x16x32_bf16 v[44:47], v[208:211], v[188:191], v[44:47]
	v_mfma_f32_16x16x32_bf16 v[48:51], v[196:199], v[192:195], v[48:51]
	v_mfma_f32_16x16x32_bf16 v[52:55], v[200:203], v[192:195], v[52:55]
	v_mfma_f32_16x16x32_bf16 v[56:59], v[204:207], v[192:195], v[56:59]
	v_mfma_f32_16x16x32_bf16 v[60:63], v[208:211], v[192:195], v[60:63]
	global_load_dwordx4 v[180:183], v128, s[4:5] offset:320
	global_load_dwordx4 v[184:187], v129, s[4:5] offset:320
	global_load_dwordx4 v[188:191], v130, s[4:5] offset:320
	global_load_dwordx4 v[192:195], v131, s[4:5] offset:320
	global_load_dwordx4 v[196:199], v132, s[6:7] offset:320
	global_load_dwordx4 v[200:203], v133, s[6:7] offset:320
	global_load_dwordx4 v[204:207], v134, s[6:7] offset:320
	global_load_dwordx4 v[208:211], v135, s[6:7] offset:320
	s_waitcnt vmcnt(16)
	v_mfma_f32_16x16x32_bf16 v[0:3], v[80:83], v[64:67], v[0:3]
	v_mfma_f32_16x16x32_bf16 v[4:7], v[84:87], v[64:67], v[4:7]
	v_mfma_f32_16x16x32_bf16 v[8:11], v[88:91], v[64:67], v[8:11]
	v_mfma_f32_16x16x32_bf16 v[12:15], v[92:95], v[64:67], v[12:15]
	v_mfma_f32_16x16x32_bf16 v[16:19], v[80:83], v[68:71], v[16:19]
	v_mfma_f32_16x16x32_bf16 v[20:23], v[84:87], v[68:71], v[20:23]
	v_mfma_f32_16x16x32_bf16 v[24:27], v[88:91], v[68:71], v[24:27]
	v_mfma_f32_16x16x32_bf16 v[28:31], v[92:95], v[68:71], v[28:31]
	v_mfma_f32_16x16x32_bf16 v[32:35], v[80:83], v[72:75], v[32:35]
	v_mfma_f32_16x16x32_bf16 v[36:39], v[84:87], v[72:75], v[36:39]
	v_mfma_f32_16x16x32_bf16 v[40:43], v[88:91], v[72:75], v[40:43]
	v_mfma_f32_16x16x32_bf16 v[44:47], v[92:95], v[72:75], v[44:47]
	v_mfma_f32_16x16x32_bf16 v[48:51], v[80:83], v[76:79], v[48:51]
	v_mfma_f32_16x16x32_bf16 v[52:55], v[84:87], v[76:79], v[52:55]
	v_mfma_f32_16x16x32_bf16 v[56:59], v[88:91], v[76:79], v[56:59]
	v_mfma_f32_16x16x32_bf16 v[60:63], v[92:95], v[76:79], v[60:63]
	global_load_dwordx4 v[64:67], v128, s[4:5] offset:384
	global_load_dwordx4 v[68:71], v129, s[4:5] offset:384
	global_load_dwordx4 v[72:75], v130, s[4:5] offset:384
	global_load_dwordx4 v[76:79], v131, s[4:5] offset:384
	global_load_dwordx4 v[80:83], v132, s[6:7] offset:384
	global_load_dwordx4 v[84:87], v133, s[6:7] offset:384
	global_load_dwordx4 v[88:91], v134, s[6:7] offset:384
	global_load_dwordx4 v[92:95], v135, s[6:7] offset:384
	s_waitcnt vmcnt(16)
	v_mfma_f32_16x16x32_bf16 v[0:3], v[112:115], v[96:99], v[0:3]
	v_mfma_f32_16x16x32_bf16 v[4:7], v[116:119], v[96:99], v[4:7]
	v_mfma_f32_16x16x32_bf16 v[8:11], v[120:123], v[96:99], v[8:11]
	v_mfma_f32_16x16x32_bf16 v[12:15], v[124:127], v[96:99], v[12:15]
	v_mfma_f32_16x16x32_bf16 v[16:19], v[112:115], v[100:103], v[16:19]
	v_mfma_f32_16x16x32_bf16 v[20:23], v[116:119], v[100:103], v[20:23]
	v_mfma_f32_16x16x32_bf16 v[24:27], v[120:123], v[100:103], v[24:27]
	v_mfma_f32_16x16x32_bf16 v[28:31], v[124:127], v[100:103], v[28:31]
	v_mfma_f32_16x16x32_bf16 v[32:35], v[112:115], v[104:107], v[32:35]
	v_mfma_f32_16x16x32_bf16 v[36:39], v[116:119], v[104:107], v[36:39]
	v_mfma_f32_16x16x32_bf16 v[40:43], v[120:123], v[104:107], v[40:43]
	v_mfma_f32_16x16x32_bf16 v[44:47], v[124:127], v[104:107], v[44:47]
	v_mfma_f32_16x16x32_bf16 v[48:51], v[112:115], v[108:111], v[48:51]
	v_mfma_f32_16x16x32_bf16 v[52:55], v[116:119], v[108:111], v[52:55]
	v_mfma_f32_16x16x32_bf16 v[56:59], v[120:123], v[108:111], v[56:59]
	v_mfma_f32_16x16x32_bf16 v[60:63], v[124:127], v[108:111], v[60:63]
	global_load_dwordx4 v[96:99], v128, s[4:5] offset:448
	global_load_dwordx4 v[100:103], v129, s[4:5] offset:448
	global_load_dwordx4 v[104:107], v130, s[4:5] offset:448
	global_load_dwordx4 v[108:111], v131, s[4:5] offset:448
	global_load_dwordx4 v[112:115], v132, s[6:7] offset:448
	global_load_dwordx4 v[116:119], v133, s[6:7] offset:448
	global_load_dwordx4 v[120:123], v134, s[6:7] offset:448
	global_load_dwordx4 v[124:127], v135, s[6:7] offset:448
	s_waitcnt vmcnt(16)
	v_mfma_f32_16x16x32_bf16 v[0:3], v[196:199], v[180:183], v[0:3]
	v_mfma_f32_16x16x32_bf16 v[4:7], v[200:203], v[180:183], v[4:7]
	v_mfma_f32_16x16x32_bf16 v[8:11], v[204:207], v[180:183], v[8:11]
	v_mfma_f32_16x16x32_bf16 v[12:15], v[208:211], v[180:183], v[12:15]
	v_mfma_f32_16x16x32_bf16 v[16:19], v[196:199], v[184:187], v[16:19]
	v_mfma_f32_16x16x32_bf16 v[20:23], v[200:203], v[184:187], v[20:23]
	v_mfma_f32_16x16x32_bf16 v[24:27], v[204:207], v[184:187], v[24:27]
	v_mfma_f32_16x16x32_bf16 v[28:31], v[208:211], v[184:187], v[28:31]
	v_mfma_f32_16x16x32_bf16 v[32:35], v[196:199], v[188:191], v[32:35]
	v_mfma_f32_16x16x32_bf16 v[36:39], v[200:203], v[188:191], v[36:39]
	v_mfma_f32_16x16x32_bf16 v[40:43], v[204:207], v[188:191], v[40:43]
	v_mfma_f32_16x16x32_bf16 v[44:47], v[208:211], v[188:191], v[44:47]
	v_mfma_f32_16x16x32_bf16 v[48:51], v[196:199], v[192:195], v[48:51]
	v_mfma_f32_16x16x32_bf16 v[52:55], v[200:203], v[192:195], v[52:55]
	v_mfma_f32_16x16x32_bf16 v[56:59], v[204:207], v[192:195], v[56:59]
	v_mfma_f32_16x16x32_bf16 v[60:63], v[208:211], v[192:195], v[60:63]
	global_load_dwordx4 v[180:183], v128, s[4:5] offset:512
	global_load_dwordx4 v[184:187], v129, s[4:5] offset:512
	global_load_dwordx4 v[188:191], v130, s[4:5] offset:512
	global_load_dwordx4 v[192:195], v131, s[4:5] offset:512
	global_load_dwordx4 v[196:199], v132, s[6:7] offset:512
	global_load_dwordx4 v[200:203], v133, s[6:7] offset:512
	global_load_dwordx4 v[204:207], v134, s[6:7] offset:512
	global_load_dwordx4 v[208:211], v135, s[6:7] offset:512
	s_waitcnt vmcnt(16)
	v_mfma_f32_16x16x32_bf16 v[0:3], v[80:83], v[64:67], v[0:3]
	v_mfma_f32_16x16x32_bf16 v[4:7], v[84:87], v[64:67], v[4:7]
	v_mfma_f32_16x16x32_bf16 v[8:11], v[88:91], v[64:67], v[8:11]
	v_mfma_f32_16x16x32_bf16 v[12:15], v[92:95], v[64:67], v[12:15]
	v_mfma_f32_16x16x32_bf16 v[16:19], v[80:83], v[68:71], v[16:19]
	v_mfma_f32_16x16x32_bf16 v[20:23], v[84:87], v[68:71], v[20:23]
	v_mfma_f32_16x16x32_bf16 v[24:27], v[88:91], v[68:71], v[24:27]
	v_mfma_f32_16x16x32_bf16 v[28:31], v[92:95], v[68:71], v[28:31]
	v_mfma_f32_16x16x32_bf16 v[32:35], v[80:83], v[72:75], v[32:35]
	v_mfma_f32_16x16x32_bf16 v[36:39], v[84:87], v[72:75], v[36:39]
	v_mfma_f32_16x16x32_bf16 v[40:43], v[88:91], v[72:75], v[40:43]
	v_mfma_f32_16x16x32_bf16 v[44:47], v[92:95], v[72:75], v[44:47]
	v_mfma_f32_16x16x32_bf16 v[48:51], v[80:83], v[76:79], v[48:51]
	v_mfma_f32_16x16x32_bf16 v[52:55], v[84:87], v[76:79], v[52:55]
	v_mfma_f32_16x16x32_bf16 v[56:59], v[88:91], v[76:79], v[56:59]
	v_mfma_f32_16x16x32_bf16 v[60:63], v[92:95], v[76:79], v[60:63]
	global_load_dwordx4 v[64:67], v128, s[4:5] offset:576
	global_load_dwordx4 v[68:71], v129, s[4:5] offset:576
	global_load_dwordx4 v[72:75], v130, s[4:5] offset:576
	global_load_dwordx4 v[76:79], v131, s[4:5] offset:576
	global_load_dwordx4 v[80:83], v132, s[6:7] offset:576
	global_load_dwordx4 v[84:87], v133, s[6:7] offset:576
	global_load_dwordx4 v[88:91], v134, s[6:7] offset:576
	global_load_dwordx4 v[92:95], v135, s[6:7] offset:576
	s_waitcnt vmcnt(16)
	v_mfma_f32_16x16x32_bf16 v[0:3], v[112:115], v[96:99], v[0:3]
	v_mfma_f32_16x16x32_bf16 v[4:7], v[116:119], v[96:99], v[4:7]
	v_mfma_f32_16x16x32_bf16 v[8:11], v[120:123], v[96:99], v[8:11]
	v_mfma_f32_16x16x32_bf16 v[12:15], v[124:127], v[96:99], v[12:15]
	v_mfma_f32_16x16x32_bf16 v[16:19], v[112:115], v[100:103], v[16:19]
	v_mfma_f32_16x16x32_bf16 v[20:23], v[116:119], v[100:103], v[20:23]
	v_mfma_f32_16x16x32_bf16 v[24:27], v[120:123], v[100:103], v[24:27]
	v_mfma_f32_16x16x32_bf16 v[28:31], v[124:127], v[100:103], v[28:31]
	v_mfma_f32_16x16x32_bf16 v[32:35], v[112:115], v[104:107], v[32:35]
	v_mfma_f32_16x16x32_bf16 v[36:39], v[116:119], v[104:107], v[36:39]
	v_mfma_f32_16x16x32_bf16 v[40:43], v[120:123], v[104:107], v[40:43]
	v_mfma_f32_16x16x32_bf16 v[44:47], v[124:127], v[104:107], v[44:47]
	v_mfma_f32_16x16x32_bf16 v[48:51], v[112:115], v[108:111], v[48:51]
	v_mfma_f32_16x16x32_bf16 v[52:55], v[116:119], v[108:111], v[52:55]
	v_mfma_f32_16x16x32_bf16 v[56:59], v[120:123], v[108:111], v[56:59]
	v_mfma_f32_16x16x32_bf16 v[60:63], v[124:127], v[108:111], v[60:63]
	global_load_dwordx4 v[96:99], v128, s[4:5] offset:640
	global_load_dwordx4 v[100:103], v129, s[4:5] offset:640
	global_load_dwordx4 v[104:107], v130, s[4:5] offset:640
	global_load_dwordx4 v[108:111], v131, s[4:5] offset:640
	global_load_dwordx4 v[112:115], v132, s[6:7] offset:640
	global_load_dwordx4 v[116:119], v133, s[6:7] offset:640
	global_load_dwordx4 v[120:123], v134, s[6:7] offset:640
	global_load_dwordx4 v[124:127], v135, s[6:7] offset:640
	s_waitcnt vmcnt(16)
	v_mfma_f32_16x16x32_bf16 v[0:3], v[196:199], v[180:183], v[0:3]
	v_mfma_f32_16x16x32_bf16 v[4:7], v[200:203], v[180:183], v[4:7]
	v_mfma_f32_16x16x32_bf16 v[8:11], v[204:207], v[180:183], v[8:11]
	v_mfma_f32_16x16x32_bf16 v[12:15], v[208:211], v[180:183], v[12:15]
	v_mfma_f32_16x16x32_bf16 v[16:19], v[196:199], v[184:187], v[16:19]
	v_mfma_f32_16x16x32_bf16 v[20:23], v[200:203], v[184:187], v[20:23]
	v_mfma_f32_16x16x32_bf16 v[24:27], v[204:207], v[184:187], v[24:27]
	v_mfma_f32_16x16x32_bf16 v[28:31], v[208:211], v[184:187], v[28:31]
	v_mfma_f32_16x16x32_bf16 v[32:35], v[196:199], v[188:191], v[32:35]
	v_mfma_f32_16x16x32_bf16 v[36:39], v[200:203], v[188:191], v[36:39]
	v_mfma_f32_16x16x32_bf16 v[40:43], v[204:207], v[188:191], v[40:43]
	v_mfma_f32_16x16x32_bf16 v[44:47], v[208:211], v[188:191], v[44:47]
	v_mfma_f32_16x16x32_bf16 v[48:51], v[196:199], v[192:195], v[48:51]
	v_mfma_f32_16x16x32_bf16 v[52:55], v[200:203], v[192:195], v[52:55]
	v_mfma_f32_16x16x32_bf16 v[56:59], v[204:207], v[192:195], v[56:59]
	v_mfma_f32_16x16x32_bf16 v[60:63], v[208:211], v[192:195], v[60:63]
	s_waitcnt vmcnt(8)
	v_mfma_f32_16x16x32_bf16 v[0:3], v[80:83], v[64:67], v[0:3]
	v_mfma_f32_16x16x32_bf16 v[4:7], v[84:87], v[64:67], v[4:7]
	v_mfma_f32_16x16x32_bf16 v[8:11], v[88:91], v[64:67], v[8:11]
	v_mfma_f32_16x16x32_bf16 v[12:15], v[92:95], v[64:67], v[12:15]
	v_mfma_f32_16x16x32_bf16 v[16:19], v[80:83], v[68:71], v[16:19]
	v_mfma_f32_16x16x32_bf16 v[20:23], v[84:87], v[68:71], v[20:23]
	v_mfma_f32_16x16x32_bf16 v[24:27], v[88:91], v[68:71], v[24:27]
	v_mfma_f32_16x16x32_bf16 v[28:31], v[92:95], v[68:71], v[28:31]
	v_mfma_f32_16x16x32_bf16 v[32:35], v[80:83], v[72:75], v[32:35]
	v_mfma_f32_16x16x32_bf16 v[36:39], v[84:87], v[72:75], v[36:39]
	v_mfma_f32_16x16x32_bf16 v[40:43], v[88:91], v[72:75], v[40:43]
	v_mfma_f32_16x16x32_bf16 v[44:47], v[92:95], v[72:75], v[44:47]
	v_mfma_f32_16x16x32_bf16 v[48:51], v[80:83], v[76:79], v[48:51]
	v_mfma_f32_16x16x32_bf16 v[52:55], v[84:87], v[76:79], v[52:55]
	v_mfma_f32_16x16x32_bf16 v[56:59], v[88:91], v[76:79], v[56:59]
	v_mfma_f32_16x16x32_bf16 v[60:63], v[92:95], v[76:79], v[60:63]
	s_waitcnt vmcnt(0)
	v_mfma_f32_16x16x32_bf16 v[0:3], v[112:115], v[96:99], v[0:3]
	v_mfma_f32_16x16x32_bf16 v[4:7], v[116:119], v[96:99], v[4:7]
	v_mfma_f32_16x16x32_bf16 v[8:11], v[120:123], v[96:99], v[8:11]
	v_mfma_f32_16x16x32_bf16 v[12:15], v[124:127], v[96:99], v[12:15]
	v_mfma_f32_16x16x32_bf16 v[16:19], v[112:115], v[100:103], v[16:19]
	v_mfma_f32_16x16x32_bf16 v[20:23], v[116:119], v[100:103], v[20:23]
	v_mfma_f32_16x16x32_bf16 v[24:27], v[120:123], v[100:103], v[24:27]
	v_mfma_f32_16x16x32_bf16 v[28:31], v[124:127], v[100:103], v[28:31]
	v_mfma_f32_16x16x32_bf16 v[32:35], v[112:115], v[104:107], v[32:35]
	v_mfma_f32_16x16x32_bf16 v[36:39], v[116:119], v[104:107], v[36:39]
	v_mfma_f32_16x16x32_bf16 v[40:43], v[120:123], v[104:107], v[40:43]
	v_mfma_f32_16x16x32_bf16 v[44:47], v[124:127], v[104:107], v[44:47]
	v_mfma_f32_16x16x32_bf16 v[48:51], v[112:115], v[108:111], v[48:51]
	v_mfma_f32_16x16x32_bf16 v[52:55], v[116:119], v[108:111], v[52:55]
	v_mfma_f32_16x16x32_bf16 v[56:59], v[120:123], v[108:111], v[56:59]
	v_mfma_f32_16x16x32_bf16 v[60:63], v[124:127], v[108:111], v[60:63]
	s_nop 7
	ds_write_b128 v136, v[0:3]
	ds_write_b128 v136, v[4:7] offset:8192
	ds_write_b128 v136, v[8:11] offset:16384
	ds_write_b128 v136, v[12:15] offset:24576
	ds_write_b128 v136, v[16:19] offset:32768
	ds_write_b128 v136, v[20:23] offset:40960
	ds_write_b128 v136, v[24:27] offset:49152
	ds_write_b128 v136, v[28:31] offset:57344
	ds_write_b128 v137, v[32:35]
	ds_write_b128 v137, v[36:39] offset:8192
	ds_write_b128 v137, v[40:43] offset:16384
	ds_write_b128 v137, v[44:47] offset:24576
	ds_write_b128 v137, v[48:51] offset:32768
	ds_write_b128 v137, v[52:55] offset:40960
	ds_write_b128 v137, v[56:59] offset:49152
	ds_write_b128 v137, v[60:63] offset:57344
	s_waitcnt lgkmcnt(0)
	s_barrier
	ds_read_b128 v[64:67], v138
	ds_read_b128 v[68:71], v138 offset:1024
	ds_read_b128 v[72:75], v138 offset:2048
	ds_read_b128 v[76:79], v138 offset:3072
	ds_read_b128 v[80:83], v138 offset:4096
	ds_read_b128 v[84:87], v138 offset:5120
	ds_read_b128 v[88:91], v138 offset:6144
	ds_read_b128 v[92:95], v138 offset:7168
	ds_read_b128 v[96:99], v138 offset:8192
	ds_read_b128 v[100:103], v138 offset:9216
	ds_read_b128 v[104:107], v138 offset:10240
	ds_read_b128 v[108:111], v138 offset:11264
	ds_read_b128 v[112:115], v138 offset:12288
	ds_read_b128 v[116:119], v138 offset:13312
	ds_read_b128 v[120:123], v138 offset:14336
	ds_read_b128 v[124:127], v138 offset:15360
	s_waitcnt lgkmcnt(0)
	v_pk_add_f32 v[64:65], v[64:65], v[68:69]
	v_pk_add_f32 v[66:67], v[66:67], v[70:71]
	v_pk_add_f32 v[96:97], v[96:97], v[100:101]
	v_pk_add_f32 v[98:99], v[98:99], v[102:103]
	v_pk_add_f32 v[64:65], v[64:65], v[72:73]
	v_pk_add_f32 v[66:67], v[66:67], v[74:75]
	v_pk_add_f32 v[96:97], v[96:97], v[104:105]
	v_pk_add_f32 v[98:99], v[98:99], v[106:107]
	v_pk_add_f32 v[64:65], v[64:65], v[76:77]
	v_pk_add_f32 v[66:67], v[66:67], v[78:79]
	v_pk_add_f32 v[96:97], v[96:97], v[108:109]
	v_pk_add_f32 v[98:99], v[98:99], v[110:111]
	v_pk_add_f32 v[64:65], v[64:65], v[80:81]
	v_pk_add_f32 v[66:67], v[66:67], v[82:83]
	v_pk_add_f32 v[96:97], v[96:97], v[112:113]
	v_pk_add_f32 v[98:99], v[98:99], v[114:115]
	v_pk_add_f32 v[64:65], v[64:65], v[84:85]
	v_pk_add_f32 v[66:67], v[66:67], v[86:87]
	v_pk_add_f32 v[96:97], v[96:97], v[116:117]
	v_pk_add_f32 v[98:99], v[98:99], v[118:119]
	v_pk_add_f32 v[64:65], v[64:65], v[88:89]
	v_pk_add_f32 v[66:67], v[66:67], v[90:91]
	v_pk_add_f32 v[96:97], v[96:97], v[120:121]
	v_pk_add_f32 v[98:99], v[98:99], v[122:123]
	v_pk_add_f32 v[64:65], v[64:65], v[92:93]
	v_pk_add_f32 v[66:67], v[66:67], v[94:95]
	v_pk_add_f32 v[96:97], v[96:97], v[124:125]
	v_pk_add_f32 v[98:99], v[98:99], v[126:127]
	s_waitcnt vmcnt(0)
	v_lshlrev_b32_e32 v140, 16, v213
	v_and_b32_e32 v141, 0xffff0000, v213
	v_and_b32_e32 v213, 0xffff0000, v212
	v_lshlrev_b32_e32 v212, 16, v212
	v_lshlrev_b32_e32 v142, 16, v215
	v_and_b32_e32 v143, 0xffff0000, v215
	v_and_b32_e32 v215, 0xffff0000, v214
	v_lshlrev_b32_e32 v214, 16, v214
	v_pk_fma_f32 v[64:65], v[212:213], s[12:13], v[64:65] op_sel_hi:[1,0,1]
	v_pk_fma_f32 v[66:67], v[140:141], s[12:13], v[66:67] op_sel_hi:[1,0,1]
	v_pk_fma_f32 v[96:97], v[214:215], s[12:13], v[96:97] op_sel_hi:[1,0,1]
	v_pk_fma_f32 v[98:99], v[142:143], s[12:13], v[98:99] op_sel_hi:[1,0,1]
	v_cvt_pk_bf16_f32 v64, v64, v65
	v_cvt_pk_bf16_f32 v65, v66, v67
	v_cvt_pk_bf16_f32 v96, v96, v97
	v_cvt_pk_bf16_f32 v97, v98, v99
	global_store_dwordx2 v139, v[64:65], s[10:11]
	global_store_dwordx2 v139, v[96:97], s[10:11] offset:32
	s_getreg_b32 s2, hwreg(HW_REG_XCC_ID, 0, 4)
	s_waitcnt vmcnt(0)
	v_mov_b32_e32 v0, v154
	s_waitcnt lgkmcnt(0)
	s_barrier
	s_nop 0
	v_cmp_eq_u32_e32 vcc, 0, v0
	s_and_saveexec_b64 s[0:1], vcc
	s_cbranch_execz .LBB0_1924
	s_add_i32 s3, 0, 0x20010
	v_mov_b32_e32 v0, s3
	s_waitcnt vmcnt(0) expcnt(0) lgkmcnt(0)
	ds_read_b32 v2, v0
	s_add_i32 s3, 0, 0x20014
	v_mov_b32_e32 v0, s3
	ds_read_b32 v0, v0
	s_and_b32 s2, s2, 15
	s_waitcnt lgkmcnt(1)
	v_cmp_ne_u32_e32 vcc, 0, v2
	s_cbranch_vccnz .LBB0_1888
	s_add_u32 s4, s36, 0x1000
	s_addc_u32 s5, s37, 0
	s_add_u32 s6, s36, 0x1100
	s_addc_u32 s7, s37, 0
	s_add_u32 s8, s36, 0x1200
	v_readlane_b32 s3, v255, 1
	s_addc_u32 s9, s37, 0
	s_mul_i32 s3, s85, s3
	s_add_u32 s10, s36, 0x1300
	s_mul_i32 s3, s3, s84
	s_addc_u32 s11, s37, 0
	s_mov_b32 s18, 1
	v_mov_b32_e32 v16, 0
	s_branch .LBB0_1876
